# v8: + dead zero-initialisations removed from the up-projection conv/gelu epilogue (192 v_mov per tile)
# speedup vs baseline: 1.0135x; 1.0062x over previous
; #define LAS __attribute__((address_space(3)))
; __device__ __forceinline__ unsigned pk2(float lo, float hi) { f32x2 v = {lo, hi}; bf16x2_t b = __builtin_convertvector(v, bf16x2_t); return __builtin_bit_cast(unsigned, b); }
; __device__ __forceinline__ float gelu_tanh(float x) {
;     const float t = x + 0.044715f * x * x * x;
;     const float e = __builtin_amdgcn_exp2f(-2.f * 0.7978845608028654f * LOG2E * t);
;     return x * __builtin_amdgcn_rcpf(1.f + e);
; }
;     __device__ __forceinline__ void operator()(const f32x4 (&acc)[2][2][4][2], const Unit& u, int wr, int wc, int fr, int fq, LAS unsigned char* lds) const {
;     ...
;                 const int trow = 64 * blk + 16 * m + fr;
;                 float og[8], ov[8];
; #pragma unroll
;                 for (int bj = 0; bj < 2; ++bj)
; #pragma unroll
;                     for (int n = 0; n < 2; ++n) {
;                         f32x4 pv, nv;
;                         if (m == 0) pv = (blk > 0) ? *(const LAS f32x4*)(XB + (2 * blk - 1) * 256 + bj * 128 + chl + 4 * n) : (f32x4){0.f, 0.f, 0.f, 0.f};
;                         if (m == 3) nv = (blk < 3) ? *(const LAS f32x4*)(XB + (2 * blk + 2) * 256 + bj * 128 + chl + 4 * n) : (f32x4){0.f, 0.f, 0.f, 0.f};
; #pragma unroll
;                         for (int e = 0; e < 4; ++e) {
;                             const float cur = acc[ai][bj][m][n][e];
;                             const float upB = (m == 0) ? pv[e] : dppf(0.f, acc[ai][bj][m == 0 ? 0 : m - 1][n][e], 0);
;                             const float dnB = (m == 3) ? nv[e] : dppf(0.f, acc[ai][bj][m == 3 ? 3 : m + 1][n][e], 1);
;                             const float up = dppf(upB, cur, 2), dn = dppf(dnB, cur, 3);
;                             const int k = 4 * n + e;
;                             if (bj == 0) og[k] = wg[0][k] * up + wg[1][k] * cur + wg[2][k] * dn;
;                             else         ov[k] = wv[0][k] * up + wv[1][k] * cur + wv[2][k] * dn;
;                         }
;                     }
;                 u32x4 ow;
; #pragma unroll
;                 for (int e2 = 0; e2 < 4; ++e2) ow[e2] = pk2(gelu_tanh(og[2 * e2]) * ov[2 * e2], gelu_tanh(og[2 * e2 + 1]) * ov[2 * e2 + 1]);
;                 if (trow != 0 && trow != 255) *(u32x4*)(ACTp + (size_t)(u.pm * BM + trow) * DFF + ch) = ow;
.LBB0_1168:
	v_mov_b32_dpp v218, v158 row_ror:15 row_mask:0xf bank_mask:0xf
	v_mov_b32_dpp v219, v159 row_ror:15 row_mask:0xf bank_mask:0xf
	v_mov_b32_dpp v220, v160 row_ror:15 row_mask:0xf bank_mask:0xf
	v_mov_b32_dpp v221, v161 row_ror:15 row_mask:0xf bank_mask:0xf
	s_waitcnt lgkmcnt(0)
	v_mov_b32_dpp v182, v174 row_shr:1 row_mask:0xf bank_mask:0xf
	v_mov_b32_dpp v218, v174 row_shl:1 row_mask:0xf bank_mask:0xf
	v_mov_b32_dpp v183, v175 row_shr:1 row_mask:0xf bank_mask:0xf
	v_mov_b32_dpp v219, v175 row_shl:1 row_mask:0xf bank_mask:0xf
	v_mov_b32_dpp v184, v176 row_shr:1 row_mask:0xf bank_mask:0xf
	v_mov_b32_dpp v220, v176 row_shl:1 row_mask:0xf bank_mask:0xf
	v_mov_b32_dpp v185, v177 row_shr:1 row_mask:0xf bank_mask:0xf
	v_mov_b32_dpp v221, v177 row_shl:1 row_mask:0xf bank_mask:0xf
	s_and_b64 vcc, exec, s[18:19]
	v_mov_b32_e32 v187, 0
	v_mov_b32_e32 v188, 0
	v_mov_b32_e32 v189, 0
	s_cbranch_vccnz .LBB0_1170
	ds_read_b128 v[186:189], v252 offset:16
.LBB0_1170:
	v_mov_b32_dpp v224, v154 row_ror:15 row_mask:0xf bank_mask:0xf
	v_mov_b32_dpp v225, v155 row_ror:15 row_mask:0xf bank_mask:0xf
	v_mov_b32_dpp v226, v156 row_ror:15 row_mask:0xf bank_mask:0xf
	v_mov_b32_dpp v227, v157 row_ror:15 row_mask:0xf bank_mask:0xf
	v_mov_b32_e32 v178, 0
	s_waitcnt lgkmcnt(0)
	v_mov_b32_dpp v186, v166 row_shr:1 row_mask:0xf bank_mask:0xf
	v_mov_b32_dpp v224, v166 row_shl:1 row_mask:0xf bank_mask:0xf
	v_mov_b32_dpp v187, v167 row_shr:1 row_mask:0xf bank_mask:0xf
	v_mov_b32_dpp v225, v167 row_shl:1 row_mask:0xf bank_mask:0xf
	v_mov_b32_dpp v188, v168 row_shr:1 row_mask:0xf bank_mask:0xf
	v_mov_b32_dpp v226, v168 row_shl:1 row_mask:0xf bank_mask:0xf
	v_mov_b32_dpp v189, v169 row_shr:1 row_mask:0xf bank_mask:0xf
	v_mov_b32_dpp v227, v169 row_shl:1 row_mask:0xf bank_mask:0xf
	s_and_b64 vcc, exec, s[18:19]
	v_mov_b32_e32 v190, 0
	v_mov_b32_e32 v191, 0
	v_mov_b32_e32 v192, 0
	v_mov_b32_e32 v193, 0
	s_cbranch_vccnz .LBB0_1172
	ds_read_b128 v[190:193], v252 offset:512
.LBB0_1172:
	v_mov_b32_dpp v230, v150 row_ror:15 row_mask:0xf bank_mask:0xf
	v_mov_b32_dpp v231, v151 row_ror:15 row_mask:0xf bank_mask:0xf
	v_mov_b32_dpp v232, v152 row_ror:15 row_mask:0xf bank_mask:0xf
	v_mov_b32_dpp v233, v153 row_ror:15 row_mask:0xf bank_mask:0xf
	s_waitcnt lgkmcnt(0)
	v_mov_b32_dpp v190, v170 row_shr:1 row_mask:0xf bank_mask:0xf
	v_mov_b32_dpp v230, v170 row_shl:1 row_mask:0xf bank_mask:0xf
	v_mov_b32_dpp v191, v171 row_shr:1 row_mask:0xf bank_mask:0xf
	v_mov_b32_dpp v231, v171 row_shl:1 row_mask:0xf bank_mask:0xf
	v_mov_b32_dpp v192, v172 row_shr:1 row_mask:0xf bank_mask:0xf
	v_mov_b32_dpp v232, v172 row_shl:1 row_mask:0xf bank_mask:0xf
	v_mov_b32_dpp v193, v173 row_shr:1 row_mask:0xf bank_mask:0xf
	v_mov_b32_dpp v233, v173 row_shl:1 row_mask:0xf bank_mask:0xf
	s_and_b64 vcc, exec, s[18:19]
	v_mov_b32_e32 v179, 0
	v_mov_b32_e32 v180, 0
	v_mov_b32_e32 v181, 0
	s_cbranch_vccnz .LBB0_1174
	ds_read_b128 v[178:181], v252 offset:528
.LBB0_1174:
	v_mov_b32_dpp v228, v146 row_ror:15 row_mask:0xf bank_mask:0xf
	v_mov_b32_dpp v229, v147 row_ror:15 row_mask:0xf bank_mask:0xf
	v_mov_b32_dpp v222, v148 row_ror:15 row_mask:0xf bank_mask:0xf
	v_mov_b32_dpp v223, v149 row_ror:15 row_mask:0xf bank_mask:0xf
	s_lshl_b32 s56, s96, 8
	s_waitcnt lgkmcnt(0)
	v_mov_b32_dpp v178, v162 row_shr:1 row_mask:0xf bank_mask:0xf
	v_mov_b32_dpp v228, v162 row_shl:1 row_mask:0xf bank_mask:0xf
	v_mov_b32_dpp v179, v163 row_shr:1 row_mask:0xf bank_mask:0xf
	v_mov_b32_dpp v229, v163 row_shl:1 row_mask:0xf bank_mask:0xf
	v_mov_b32_dpp v180, v164 row_shr:1 row_mask:0xf bank_mask:0xf
	v_mov_b32_dpp v222, v164 row_shl:1 row_mask:0xf bank_mask:0xf
	v_mov_b32_dpp v181, v165 row_shr:1 row_mask:0xf bank_mask:0xf
	v_mov_b32_dpp v223, v165 row_shl:1 row_mask:0xf bank_mask:0xf
	s_and_saveexec_b64 s[18:19], s[8:9]
	s_xor_b64 s[18:19], exec, s[18:19]
	s_cbranch_execz .LBB0_1176
	s_waitcnt vmcnt(0)
	v_pk_mul_f32 v[234:235], v[170:171], v[108:109]
	v_pk_mul_f32 v[242:243], v[172:173], v[110:111]
	v_pk_fma_f32 v[190:191], v[100:101], v[190:191], v[234:235]
	v_pk_fma_f32 v[192:193], v[102:103], v[192:193], v[242:243]
	v_pk_fma_f32 v[190:191], v[104:105], v[230:231], v[190:191]
	v_pk_mul_f32 v[230:231], v[168:169], v[98:99]
	v_pk_fma_f32 v[192:193], v[106:107], v[232:233], v[192:193]
	v_pk_fma_f32 v[188:189], v[90:91], v[188:189], v[230:231]
	v_pk_mul_f32 v[232:233], v[166:167], v[96:97]
	v_pk_fma_f32 v[188:189], v[94:95], v[226:227], v[188:189]
	v_pk_mul_f32 v[226:227], v[174:175], v[84:85]
	v_pk_fma_f32 v[186:187], v[88:89], v[186:187], v[232:233]
	v_pk_fma_f32 v[182:183], v[76:77], v[182:183], v[226:227]
	v_pk_fma_f32 v[186:187], v[92:93], v[224:225], v[186:187]
	v_pk_fma_f32 v[182:183], v[80:81], v[218:219], v[182:183]
	v_pk_mul_f32 v[224:225], v[176:177], v[86:87]
	v_mul_f32_e32 v112, 0x3d372713, v182
	v_mul_f32_e32 v112, v182, v112
	v_mul_f32_e32 v215, 0x3d372713, v183
	v_fma_f32 v112, v182, v112, v182
	v_mul_f32_e32 v215, v183, v215
	v_mul_f32_e32 v112, 0xc0135761, v112
	v_fma_f32 v215, v183, v215, v183
	v_exp_f32_e32 v112, v112
	v_mul_f32_e32 v215, 0xc0135761, v215
	v_exp_f32_e32 v215, v215
	v_pk_fma_f32 v[184:185], v[78:79], v[184:185], v[224:225]
	v_add_f32_e32 v112, 1.0, v112
	v_pk_fma_f32 v[184:185], v[82:83], v[220:221], v[184:185]
	v_rcp_f32_e32 v224, v112
	v_add_f32_e32 v112, 1.0, v215
	v_mul_f32_e32 v215, 0x3d372713, v184
	v_mul_f32_e32 v215, v184, v215
	v_mul_f32_e32 v225, 0x3d372713, v185
	v_fma_f32 v215, v184, v215, v184
	v_mul_f32_e32 v225, v185, v225
	v_mul_f32_e32 v215, 0xc0135761, v215
	v_fma_f32 v225, v185, v225, v185
	v_exp_f32_e32 v215, v215
	v_mul_f32_e32 v225, 0xc0135761, v225
	v_exp_f32_e32 v227, v225
; #define LAS __attribute__((address_space(3)))
; __device__ __forceinline__ unsigned pk2(float lo, float hi) { f32x2 v = {lo, hi}; bf16x2_t b = __builtin_convertvector(v, bf16x2_t); return __builtin_bit_cast(unsigned, b); }
; __device__ __forceinline__ float gelu_tanh(float x) {
;     const float t = x + 0.044715f * x * x * x;
;     const float e = __builtin_amdgcn_exp2f(-2.f * 0.7978845608028654f * LOG2E * t);
;     return x * __builtin_amdgcn_rcpf(1.f + e);
; }
;     __device__ __forceinline__ void operator()(const f32x4 (&acc)[2][2][4][2], const Unit& u, int wr, int wc, int fr, int fq, LAS unsigned char* lds) const {
;     ...
;                 const int trow = 64 * blk + 16 * m + fr;
;                 float og[8], ov[8];
; #pragma unroll
;                 for (int bj = 0; bj < 2; ++bj)
; #pragma unroll
;                     for (int n = 0; n < 2; ++n) {
;                         f32x4 pv, nv;
;                         if (m == 0) pv = (blk > 0) ? *(const LAS f32x4*)(XB + (2 * blk - 1) * 256 + bj * 128 + chl + 4 * n) : (f32x4){0.f, 0.f, 0.f, 0.f};
;                         if (m == 3) nv = (blk < 3) ? *(const LAS f32x4*)(XB + (2 * blk + 2) * 256 + bj * 128 + chl + 4 * n) : (f32x4){0.f, 0.f, 0.f, 0.f};
; #pragma unroll
;                         for (int e = 0; e < 4; ++e) {
;                             const float cur = acc[ai][bj][m][n][e];
;                             const float upB = (m == 0) ? pv[e] : dppf(0.f, acc[ai][bj][m == 0 ? 0 : m - 1][n][e], 0);
;                             const float dnB = (m == 3) ? nv[e] : dppf(0.f, acc[ai][bj][m == 3 ? 3 : m + 1][n][e], 1);
;                             const float up = dppf(upB, cur, 2), dn = dppf(dnB, cur, 3);
;                             const int k = 4 * n + e;
;                             if (bj == 0) og[k] = wg[0][k] * up + wg[1][k] * cur + wg[2][k] * dn;
;                             else         ov[k] = wv[0][k] * up + wv[1][k] * cur + wv[2][k] * dn;
;                         }
;                     }
;                 u32x4 ow;
; #pragma unroll
;                 for (int e2 = 0; e2 < 4; ++e2) ow[e2] = pk2(gelu_tanh(og[2 * e2]) * ov[2 * e2], gelu_tanh(og[2 * e2 + 1]) * ov[2 * e2 + 1]);
;                 if (trow != 0 && trow != 255) *(u32x4*)(ACTp + (size_t)(u.pm * BM + trow) * DFF + ch) = ow;
	v_rcp_f32_e32 v225, v112
	v_add_f32_e32 v112, 1.0, v215
	v_rcp_f32_e32 v226, v112
	v_add_f32_e32 v112, 1.0, v227
	v_pk_mul_f32 v[182:183], v[182:183], v[224:225]
	v_rcp_f32_e32 v227, v112
	v_pk_mul_f32 v[182:183], v[182:183], v[190:191]
	v_mul_f32_e32 v112, 0x3d372713, v186
	v_cvt_pk_bf16_f32 v182, v182, v183
	v_mul_f32_e32 v112, v186, v112
	v_mul_f32_e32 v183, 0x3d372713, v187
	v_fma_f32 v112, v186, v112, v186
	v_mul_f32_e32 v183, v187, v183
	v_mul_f32_e32 v112, 0xc0135761, v112
	v_fma_f32 v183, v187, v183, v187
	v_exp_f32_e32 v112, v112
	v_mul_f32_e32 v183, 0xc0135761, v183
	v_exp_f32_e32 v183, v183
	v_pk_mul_f32 v[184:185], v[184:185], v[226:227]
	v_add_f32_e32 v112, 1.0, v112
	v_rcp_f32_e32 v190, v112
	v_add_f32_e32 v112, 1.0, v183
	v_rcp_f32_e32 v191, v112
	v_pk_mul_f32 v[184:185], v[184:185], v[192:193]
	v_mul_f32_e32 v112, 0x3d372713, v188
	v_cvt_pk_bf16_f32 v183, v184, v185
	v_pk_mul_f32 v[184:185], v[186:187], v[190:191]
	v_mul_f32_e32 v112, v188, v112
	v_mul_f32_e32 v186, 0x3d372713, v189
	v_fma_f32 v112, v188, v112, v188
	v_mul_f32_e32 v186, v189, v186
	v_mul_f32_e32 v112, 0xc0135761, v112
	v_fma_f32 v186, v189, v186, v189
	v_exp_f32_e32 v112, v112
	v_mul_f32_e32 v186, 0xc0135761, v186
	v_exp_f32_e32 v187, v186
	v_pk_mul_f32 v[220:221], v[162:163], v[72:73]
	v_add_f32_e32 v112, 1.0, v112
	v_rcp_f32_e32 v186, v112
	v_add_f32_e32 v112, 1.0, v187
	v_pk_fma_f32 v[178:179], v[64:65], v[178:179], v[220:221]
	v_rcp_f32_e32 v187, v112
	v_pk_fma_f32 v[178:179], v[68:69], v[228:229], v[178:179]
	v_pk_mul_f32 v[218:219], v[164:165], v[74:75]
	v_pk_mul_f32 v[178:179], v[184:185], v[178:179]
	v_add_u32_e32 v112, s56, v244
	v_cvt_pk_bf16_f32 v184, v178, v179
	v_pk_fma_f32 v[178:179], v[66:67], v[180:181], v[218:219]
	v_pk_mul_f32 v[180:181], v[188:189], v[186:187]
	v_pk_fma_f32 v[178:179], v[70:71], v[222:223], v[178:179]
	s_nop 0
	v_pk_mul_f32 v[178:179], v[180:181], v[178:179]
	s_nop 0
	v_cvt_pk_bf16_f32 v185, v178, v179
	v_mov_b64_e32 v[178:179], s[88:89]
	v_mad_i64_i32 v[178:179], s[54:55], v112, s80, v[178:179]
	v_lshl_add_u64 v[178:179], v[216:217], 1, v[178:179]
	global_store_dwordx4 v[178:179], v[182:185], off
.LBB0_1176:
	s_andn2_saveexec_b64 s[18:19], s[18:19]
	s_or_b64 exec, exec, s[18:19]
	s_waitcnt vmcnt(0)
	v_pk_mul_f32 v[222:223], v[158:159], v[84:85]
	v_mov_b32_dpp v180, v174 row_ror:1 row_mask:0xf bank_mask:0xf
	v_mov_b32_dpp v181, v175 row_ror:1 row_mask:0xf bank_mask:0xf
	v_mov_b32_dpp v174, v142 row_ror:15 row_mask:0xf bank_mask:0xf
	v_mov_b32_dpp v180, v158 row_shr:1 row_mask:0xf bank_mask:0xf
	v_mov_b32_dpp v175, v143 row_ror:15 row_mask:0xf bank_mask:0xf
	v_mov_b32_dpp v181, v159 row_shr:1 row_mask:0xf bank_mask:0xf
	v_mov_b32_dpp v174, v158 row_shl:1 row_mask:0xf bank_mask:0xf
	v_mov_b32_dpp v175, v159 row_shl:1 row_mask:0xf bank_mask:0xf
	v_pk_fma_f32 v[180:181], v[76:77], v[180:181], v[222:223]
	v_pk_fma_f32 v[174:175], v[80:81], v[174:175], v[180:181]
	v_mul_f32_e32 v112, 0x3d372713, v174
	v_mul_f32_e32 v112, v174, v112
	v_mul_f32_e32 v179, 0x3d372713, v175
	v_fma_f32 v112, v174, v112, v174
	v_mul_f32_e32 v179, v175, v179
	v_mov_b32_dpp v184, v166 row_ror:1 row_mask:0xf bank_mask:0xf
	v_mov_b32_dpp v185, v167 row_ror:1 row_mask:0xf bank_mask:0xf
	v_mul_f32_e32 v112, 0xc0135761, v112
	v_fma_f32 v179, v175, v179, v175
	v_mov_b32_dpp v166, v170 row_ror:1 row_mask:0xf bank_mask:0xf
	v_mov_b32_dpp v167, v171 row_ror:1 row_mask:0xf bank_mask:0xf
	v_exp_f32_e32 v112, v112
	v_mul_f32_e32 v179, 0xc0135761, v179
	v_mov_b32_dpp v170, v134 row_ror:15 row_mask:0xf bank_mask:0xf
	v_mov_b32_dpp v166, v150 row_shr:1 row_mask:0xf bank_mask:0xf
	v_mov_b32_dpp v171, v135 row_ror:15 row_mask:0xf bank_mask:0xf
	v_mov_b32_dpp v167, v151 row_shr:1 row_mask:0xf bank_mask:0xf
	v_exp_f32_e32 v179, v179
	v_pk_mul_f32 v[180:181], v[150:151], v[108:109]
	v_mov_b32_dpp v182, v176 row_ror:1 row_mask:0xf bank_mask:0xf
	v_mov_b32_dpp v183, v177 row_ror:1 row_mask:0xf bank_mask:0xf
	v_mov_b32_dpp v170, v150 row_shl:1 row_mask:0xf bank_mask:0xf
	v_mov_b32_dpp v171, v151 row_shl:1 row_mask:0xf bank_mask:0xf
	v_pk_fma_f32 v[166:167], v[100:101], v[166:167], v[180:181]
	v_mov_b32_dpp v176, v144 row_ror:15 row_mask:0xf bank_mask:0xf
	v_mov_b32_dpp v182, v160 row_shr:1 row_mask:0xf bank_mask:0xf
	v_mov_b32_dpp v177, v145 row_ror:15 row_mask:0xf bank_mask:0xf
	v_mov_b32_dpp v183, v161 row_shr:1 row_mask:0xf bank_mask:0xf
	v_pk_fma_f32 v[166:167], v[104:105], v[170:171], v[166:167]
	v_pk_mul_f32 v[170:171], v[160:161], v[86:87]
	v_mov_b32_dpp v176, v160 row_shl:1 row_mask:0xf bank_mask:0xf
	v_mov_b32_dpp v177, v161 row_shl:1 row_mask:0xf bank_mask:0xf
	v_add_f32_e32 v112, 1.0, v112
	v_pk_fma_f32 v[170:171], v[78:79], v[182:183], v[170:171]
	v_rcp_f32_e32 v222, v112
	v_add_f32_e32 v112, 1.0, v179
	v_pk_fma_f32 v[170:171], v[82:83], v[176:177], v[170:171]
	v_rcp_f32_e32 v223, v112
	v_mul_f32_e32 v112, 0x3d372713, v170
	v_mul_f32_e32 v112, v170, v112
	v_mul_f32_e32 v176, 0x3d372713, v171
	v_fma_f32 v112, v170, v112, v170
	v_mul_f32_e32 v176, v171, v176
	v_mul_f32_e32 v112, 0xc0135761, v112
	v_fma_f32 v176, v171, v176, v171
	v_exp_f32_e32 v112, v112
	v_mul_f32_e32 v176, 0xc0135761, v176
	v_exp_f32_e32 v176, v176
	v_pk_mul_f32 v[174:175], v[174:175], v[222:223]
	v_add_f32_e32 v112, 1.0, v112
	v_pk_mul_f32 v[166:167], v[174:175], v[166:167]
	v_rcp_f32_e32 v174, v112
	v_add_f32_e32 v112, 1.0, v176
	v_rcp_f32_e32 v175, v112
	v_mov_b32_dpp v190, v172 row_ror:1 row_mask:0xf bank_mask:0xf
	v_mov_b32_dpp v191, v173 row_ror:1 row_mask:0xf bank_mask:0xf
	v_mov_b32_dpp v172, v136 row_ror:15 row_mask:0xf bank_mask:0xf
	v_mov_b32_dpp v190, v152 row_shr:1 row_mask:0xf bank_mask:0xf
; #define LAS __attribute__((address_space(3)))
; __device__ __forceinline__ unsigned pk2(float lo, float hi) { f32x2 v = {lo, hi}; bf16x2_t b = __builtin_convertvector(v, bf16x2_t); return __builtin_bit_cast(unsigned, b); }
; __device__ __forceinline__ float gelu_tanh(float x) {
;     const float t = x + 0.044715f * x * x * x;
;     const float e = __builtin_amdgcn_exp2f(-2.f * 0.7978845608028654f * LOG2E * t);
;     return x * __builtin_amdgcn_rcpf(1.f + e);
; }
;     __device__ __forceinline__ void operator()(const f32x4 (&acc)[2][2][4][2], const Unit& u, int wr, int wc, int fr, int fq, LAS unsigned char* lds) const {
;     ...
;                 const int trow = 64 * blk + 16 * m + fr;
;                 float og[8], ov[8];
; #pragma unroll
;                 for (int bj = 0; bj < 2; ++bj)
; #pragma unroll
;                     for (int n = 0; n < 2; ++n) {
;                         f32x4 pv, nv;
;                         if (m == 0) pv = (blk > 0) ? *(const LAS f32x4*)(XB + (2 * blk - 1) * 256 + bj * 128 + chl + 4 * n) : (f32x4){0.f, 0.f, 0.f, 0.f};
;                         if (m == 3) nv = (blk < 3) ? *(const LAS f32x4*)(XB + (2 * blk + 2) * 256 + bj * 128 + chl + 4 * n) : (f32x4){0.f, 0.f, 0.f, 0.f};
; #pragma unroll
;                         for (int e = 0; e < 4; ++e) {
;                             const float cur = acc[ai][bj][m][n][e];
;                             const float upB = (m == 0) ? pv[e] : dppf(0.f, acc[ai][bj][m == 0 ? 0 : m - 1][n][e], 0);
;                             const float dnB = (m == 3) ? nv[e] : dppf(0.f, acc[ai][bj][m == 3 ? 3 : m + 1][n][e], 1);
;                             const float up = dppf(upB, cur, 2), dn = dppf(dnB, cur, 3);
;                             const int k = 4 * n + e;
;                             if (bj == 0) og[k] = wg[0][k] * up + wg[1][k] * cur + wg[2][k] * dn;
;                             else         ov[k] = wv[0][k] * up + wv[1][k] * cur + wv[2][k] * dn;
;                         }
;                     }
;                 u32x4 ow;
; #pragma unroll
;                 for (int e2 = 0; e2 < 4; ++e2) ow[e2] = pk2(gelu_tanh(og[2 * e2]) * ov[2 * e2], gelu_tanh(og[2 * e2 + 1]) * ov[2 * e2 + 1]);
;                 if (trow != 0 && trow != 255) *(u32x4*)(ACTp + (size_t)(u.pm * BM + trow) * DFF + ch) = ow;
	v_mov_b32_dpp v173, v137 row_ror:15 row_mask:0xf bank_mask:0xf
	v_mov_b32_dpp v191, v153 row_shr:1 row_mask:0xf bank_mask:0xf
	v_pk_mul_f32 v[220:221], v[152:153], v[110:111]
	v_mov_b32_dpp v172, v152 row_shl:1 row_mask:0xf bank_mask:0xf
	v_mov_b32_dpp v173, v153 row_shl:1 row_mask:0xf bank_mask:0xf
	v_pk_fma_f32 v[176:177], v[102:103], v[190:191], v[220:221]
	v_pk_fma_f32 v[172:173], v[106:107], v[172:173], v[176:177]
	v_pk_mul_f32 v[170:171], v[170:171], v[174:175]
	v_mov_b32_dpp v186, v138 row_ror:15 row_mask:0xf bank_mask:0xf
	v_mov_b32_dpp v184, v154 row_shr:1 row_mask:0xf bank_mask:0xf
	v_mov_b32_dpp v187, v139 row_ror:15 row_mask:0xf bank_mask:0xf
	v_mov_b32_dpp v185, v155 row_shr:1 row_mask:0xf bank_mask:0xf
	v_pk_mul_f32 v[170:171], v[170:171], v[172:173]
	v_pk_mul_f32 v[172:173], v[154:155], v[96:97]
	v_mov_b32_dpp v186, v154 row_shl:1 row_mask:0xf bank_mask:0xf
	v_mov_b32_dpp v187, v155 row_shl:1 row_mask:0xf bank_mask:0xf
	v_pk_fma_f32 v[172:173], v[88:89], v[184:185], v[172:173]
	v_pk_fma_f32 v[172:173], v[92:93], v[186:187], v[172:173]
	v_mul_f32_e32 v112, 0x3d372713, v172
	v_mul_f32_e32 v112, v172, v112
	v_mul_f32_e32 v174, 0x3d372713, v173
	v_fma_f32 v112, v172, v112, v172
	v_mul_f32_e32 v174, v173, v174
	v_mul_f32_e32 v112, 0xc0135761, v112
	v_fma_f32 v174, v173, v174, v173
	v_mov_b32_dpp v192, v162 row_ror:1 row_mask:0xf bank_mask:0xf
	v_mov_b32_dpp v193, v163 row_ror:1 row_mask:0xf bank_mask:0xf
	v_exp_f32_e32 v112, v112
	v_mul_f32_e32 v174, 0xc0135761, v174
	v_mov_b32_dpp v162, v130 row_ror:15 row_mask:0xf bank_mask:0xf
	v_mov_b32_dpp v192, v146 row_shr:1 row_mask:0xf bank_mask:0xf
	v_mov_b32_dpp v163, v131 row_ror:15 row_mask:0xf bank_mask:0xf
	v_mov_b32_dpp v193, v147 row_shr:1 row_mask:0xf bank_mask:0xf
	v_exp_f32_e32 v177, v174
	v_pk_mul_f32 v[174:175], v[146:147], v[72:73]
	v_mov_b32_dpp v188, v168 row_ror:1 row_mask:0xf bank_mask:0xf
	v_mov_b32_dpp v189, v169 row_ror:1 row_mask:0xf bank_mask:0xf
	v_mov_b32_dpp v162, v146 row_shl:1 row_mask:0xf bank_mask:0xf
	v_mov_b32_dpp v163, v147 row_shl:1 row_mask:0xf bank_mask:0xf
	v_pk_fma_f32 v[174:175], v[64:65], v[192:193], v[174:175]
	v_mov_b32_dpp v168, v140 row_ror:15 row_mask:0xf bank_mask:0xf
	v_mov_b32_dpp v188, v156 row_shr:1 row_mask:0xf bank_mask:0xf
	v_mov_b32_dpp v169, v141 row_ror:15 row_mask:0xf bank_mask:0xf
	v_mov_b32_dpp v189, v157 row_shr:1 row_mask:0xf bank_mask:0xf
	v_pk_fma_f32 v[162:163], v[68:69], v[162:163], v[174:175]
	v_pk_mul_f32 v[174:175], v[156:157], v[98:99]
	v_mov_b32_dpp v168, v156 row_shl:1 row_mask:0xf bank_mask:0xf
	v_mov_b32_dpp v169, v157 row_shl:1 row_mask:0xf bank_mask:0xf
	v_add_f32_e32 v112, 1.0, v112
	v_pk_fma_f32 v[174:175], v[90:91], v[188:189], v[174:175]
	v_rcp_f32_e32 v176, v112
	v_add_f32_e32 v112, 1.0, v177
	v_pk_fma_f32 v[174:175], v[94:95], v[168:169], v[174:175]
	v_rcp_f32_e32 v177, v112
	v_mul_f32_e32 v112, 0x3d372713, v174
	v_mul_f32_e32 v112, v174, v112
	v_mul_f32_e32 v168, 0x3d372713, v175
	v_fma_f32 v112, v174, v112, v174
	v_mul_f32_e32 v168, v175, v168
	v_mul_f32_e32 v112, 0xc0135761, v112
	v_fma_f32 v168, v175, v168, v175
	v_exp_f32_e32 v112, v112
	v_mul_f32_e32 v168, 0xc0135761, v168
	v_exp_f32_e32 v168, v168
	v_pk_mul_f32 v[172:173], v[172:173], v[176:177]
	v_add_f32_e32 v112, 1.0, v112
	v_pk_mul_f32 v[162:163], v[172:173], v[162:163]
	v_rcp_f32_e32 v172, v112
	v_add_f32_e32 v112, 1.0, v168
	v_rcp_f32_e32 v173, v112
	v_mov_b32_dpp v218, v164 row_ror:1 row_mask:0xf bank_mask:0xf
	v_mov_b32_dpp v219, v165 row_ror:1 row_mask:0xf bank_mask:0xf
	v_mov_b32_dpp v164, v132 row_ror:15 row_mask:0xf bank_mask:0xf
	v_mov_b32_dpp v218, v148 row_shr:1 row_mask:0xf bank_mask:0xf
	v_mov_b32_dpp v165, v133 row_ror:15 row_mask:0xf bank_mask:0xf
	v_mov_b32_dpp v219, v149 row_shr:1 row_mask:0xf bank_mask:0xf
	v_cvt_pk_bf16_f32 v166, v166, v167
	v_cvt_pk_bf16_f32 v167, v170, v171
	v_pk_mul_f32 v[170:171], v[148:149], v[74:75]
	v_mov_b32_dpp v164, v148 row_shl:1 row_mask:0xf bank_mask:0xf
	v_mov_b32_dpp v165, v149 row_shl:1 row_mask:0xf bank_mask:0xf
	v_cvt_pk_bf16_f32 v168, v162, v163
	v_pk_fma_f32 v[162:163], v[66:67], v[218:219], v[170:171]
	v_or_b32_e32 v112, 16, v244
	v_pk_fma_f32 v[162:163], v[70:71], v[164:165], v[162:163]
	v_pk_mul_f32 v[164:165], v[174:175], v[172:173]
	v_add_u32_e32 v112, s56, v112
	v_pk_mul_f32 v[162:163], v[164:165], v[162:163]
	v_mov_b64_e32 v[164:165], s[88:89]
	v_cvt_pk_bf16_f32 v169, v162, v163
	v_mad_i64_i32 v[170:171], s[18:19], v112, s80, v[164:165]
	v_lshlrev_b64 v[162:163], 1, v[216:217]
	v_lshl_add_u64 v[170:171], v[170:171], 0, v[162:163]
	global_store_dwordx4 v[170:171], v[166:169], off
	v_mov_b32_dpp v180, v146 row_ror:1 row_mask:0xf bank_mask:0xf
	v_mov_b32_dpp v166, v158 row_ror:1 row_mask:0xf bank_mask:0xf
	v_mov_b32_dpp v167, v159 row_ror:1 row_mask:0xf bank_mask:0xf
	v_mov_b32_dpp v158, v122 row_ror:15 row_mask:0xf bank_mask:0xf
	v_mov_b32_dpp v166, v142 row_shr:1 row_mask:0xf bank_mask:0xf
	v_mov_b32_dpp v159, v123 row_ror:15 row_mask:0xf bank_mask:0xf
	v_mov_b32_dpp v167, v143 row_shr:1 row_mask:0xf bank_mask:0xf
	v_mov_b32_dpp v181, v147 row_ror:1 row_mask:0xf bank_mask:0xf
	v_pk_mul_f32 v[146:147], v[142:143], v[84:85]
	v_mov_b32_dpp v158, v142 row_shl:1 row_mask:0xf bank_mask:0xf
	v_mov_b32_dpp v159, v143 row_shl:1 row_mask:0xf bank_mask:0xf
	v_pk_fma_f32 v[146:147], v[76:77], v[166:167], v[146:147]
	v_pk_fma_f32 v[146:147], v[80:81], v[158:159], v[146:147]
	v_mul_f32_e32 v112, 0x3d372713, v146
	v_mul_f32_e32 v112, v146, v112
	v_mul_f32_e32 v158, 0x3d372713, v147
	v_fma_f32 v112, v146, v112, v146
	v_mul_f32_e32 v158, v147, v158
	v_mul_f32_e32 v112, 0xc0135761, v112
; #define LAS __attribute__((address_space(3)))
; __device__ __forceinline__ unsigned pk2(float lo, float hi) { f32x2 v = {lo, hi}; bf16x2_t b = __builtin_convertvector(v, bf16x2_t); return __builtin_bit_cast(unsigned, b); }
; __device__ __forceinline__ float gelu_tanh(float x) {
;     const float t = x + 0.044715f * x * x * x;
;     const float e = __builtin_amdgcn_exp2f(-2.f * 0.7978845608028654f * LOG2E * t);
;     return x * __builtin_amdgcn_rcpf(1.f + e);
; }
;     __device__ __forceinline__ void operator()(const f32x4 (&acc)[2][2][4][2], const Unit& u, int wr, int wc, int fr, int fq, LAS unsigned char* lds) const {
;     ...
;                 const int trow = 64 * blk + 16 * m + fr;
;                 float og[8], ov[8];
; #pragma unroll
;                 for (int bj = 0; bj < 2; ++bj)
; #pragma unroll
;                     for (int n = 0; n < 2; ++n) {
;                         f32x4 pv, nv;
;                         if (m == 0) pv = (blk > 0) ? *(const LAS f32x4*)(XB + (2 * blk - 1) * 256 + bj * 128 + chl + 4 * n) : (f32x4){0.f, 0.f, 0.f, 0.f};
;                         if (m == 3) nv = (blk < 3) ? *(const LAS f32x4*)(XB + (2 * blk + 2) * 256 + bj * 128 + chl + 4 * n) : (f32x4){0.f, 0.f, 0.f, 0.f};
; #pragma unroll
;                         for (int e = 0; e < 4; ++e) {
;                             const float cur = acc[ai][bj][m][n][e];
;                             const float upB = (m == 0) ? pv[e] : dppf(0.f, acc[ai][bj][m == 0 ? 0 : m - 1][n][e], 0);
;                             const float dnB = (m == 3) ? nv[e] : dppf(0.f, acc[ai][bj][m == 3 ? 3 : m + 1][n][e], 1);
;                             const float up = dppf(upB, cur, 2), dn = dppf(dnB, cur, 3);
;                             const int k = 4 * n + e;
;                             if (bj == 0) og[k] = wg[0][k] * up + wg[1][k] * cur + wg[2][k] * dn;
;                             else         ov[k] = wv[0][k] * up + wv[1][k] * cur + wv[2][k] * dn;
;                         }
;                     }
;                 u32x4 ow;
; #pragma unroll
;                 for (int e2 = 0; e2 < 4; ++e2) ow[e2] = pk2(gelu_tanh(og[2 * e2]) * ov[2 * e2], gelu_tanh(og[2 * e2 + 1]) * ov[2 * e2 + 1]);
;                 if (trow != 0 && trow != 255) *(u32x4*)(ACTp + (size_t)(u.pm * BM + trow) * DFF + ch) = ow;
	v_fma_f32 v158, v147, v158, v147
	v_mov_b32_dpp v174, v150 row_ror:1 row_mask:0xf bank_mask:0xf
	v_mov_b32_dpp v175, v151 row_ror:1 row_mask:0xf bank_mask:0xf
	v_exp_f32_e32 v112, v112
	v_mul_f32_e32 v158, 0xc0135761, v158
	v_mov_b32_dpp v150, v126 row_ror:15 row_mask:0xf bank_mask:0xf
	v_mov_b32_dpp v174, v134 row_shr:1 row_mask:0xf bank_mask:0xf
	v_mov_b32_dpp v151, v127 row_ror:15 row_mask:0xf bank_mask:0xf
	v_mov_b32_dpp v175, v135 row_shr:1 row_mask:0xf bank_mask:0xf
	v_exp_f32_e32 v167, v158
	v_pk_mul_f32 v[158:159], v[134:135], v[108:109]
	v_mov_b32_dpp v168, v160 row_ror:1 row_mask:0xf bank_mask:0xf
	v_mov_b32_dpp v169, v161 row_ror:1 row_mask:0xf bank_mask:0xf
	v_mov_b32_dpp v150, v134 row_shl:1 row_mask:0xf bank_mask:0xf
	v_mov_b32_dpp v151, v135 row_shl:1 row_mask:0xf bank_mask:0xf
	v_pk_fma_f32 v[158:159], v[100:101], v[174:175], v[158:159]
	v_mov_b32_dpp v160, v124 row_ror:15 row_mask:0xf bank_mask:0xf
	v_mov_b32_dpp v168, v144 row_shr:1 row_mask:0xf bank_mask:0xf
	v_mov_b32_dpp v161, v125 row_ror:15 row_mask:0xf bank_mask:0xf
	v_mov_b32_dpp v169, v145 row_shr:1 row_mask:0xf bank_mask:0xf
	v_pk_fma_f32 v[150:151], v[104:105], v[150:151], v[158:159]
	v_pk_mul_f32 v[158:159], v[144:145], v[86:87]
	v_mov_b32_dpp v160, v144 row_shl:1 row_mask:0xf bank_mask:0xf
	v_mov_b32_dpp v161, v145 row_shl:1 row_mask:0xf bank_mask:0xf
	v_add_f32_e32 v112, 1.0, v112
	v_pk_fma_f32 v[158:159], v[78:79], v[168:169], v[158:159]
	v_rcp_f32_e32 v166, v112
	v_add_f32_e32 v112, 1.0, v167
	v_pk_fma_f32 v[158:159], v[82:83], v[160:161], v[158:159]
	v_rcp_f32_e32 v167, v112
	v_mul_f32_e32 v112, 0x3d372713, v158
	v_mul_f32_e32 v112, v158, v112
	v_mul_f32_e32 v160, 0x3d372713, v159
	v_fma_f32 v112, v158, v112, v158
	v_mul_f32_e32 v160, v159, v160
	v_mul_f32_e32 v112, 0xc0135761, v112
	v_fma_f32 v160, v159, v160, v159
	v_exp_f32_e32 v112, v112
	v_mul_f32_e32 v160, 0xc0135761, v160
	v_exp_f32_e32 v160, v160
	v_pk_mul_f32 v[146:147], v[146:147], v[166:167]
	v_add_f32_e32 v112, 1.0, v112
	v_pk_mul_f32 v[146:147], v[146:147], v[150:151]
	v_rcp_f32_e32 v150, v112
	v_add_f32_e32 v112, 1.0, v160
	v_rcp_f32_e32 v151, v112
	v_mov_b32_dpp v176, v152 row_ror:1 row_mask:0xf bank_mask:0xf
	v_mov_b32_dpp v177, v153 row_ror:1 row_mask:0xf bank_mask:0xf
	v_mov_b32_dpp v152, v128 row_ror:15 row_mask:0xf bank_mask:0xf
	v_mov_b32_dpp v176, v136 row_shr:1 row_mask:0xf bank_mask:0xf
	v_mov_b32_dpp v153, v129 row_ror:15 row_mask:0xf bank_mask:0xf
	v_mov_b32_dpp v177, v137 row_shr:1 row_mask:0xf bank_mask:0xf
	v_mov_b32_dpp v184, v148 row_ror:1 row_mask:0xf bank_mask:0xf
	v_mov_b32_dpp v185, v149 row_ror:1 row_mask:0xf bank_mask:0xf
	v_pk_mul_f32 v[148:149], v[136:137], v[110:111]
	v_mov_b32_dpp v152, v136 row_shl:1 row_mask:0xf bank_mask:0xf
	v_mov_b32_dpp v153, v137 row_shl:1 row_mask:0xf bank_mask:0xf
	v_pk_fma_f32 v[148:149], v[102:103], v[176:177], v[148:149]
	v_pk_fma_f32 v[148:149], v[106:107], v[152:153], v[148:149]
	v_pk_mul_f32 v[150:151], v[158:159], v[150:151]
	v_mov_b32_dpp v170, v154 row_ror:1 row_mask:0xf bank_mask:0xf
	v_mov_b32_dpp v171, v155 row_ror:1 row_mask:0xf bank_mask:0xf
	v_pk_mul_f32 v[148:149], v[150:151], v[148:149]
	v_mov_b32_dpp v154, v118 row_ror:15 row_mask:0xf bank_mask:0xf
	v_mov_b32_dpp v170, v138 row_shr:1 row_mask:0xf bank_mask:0xf
	v_mov_b32_dpp v155, v119 row_ror:15 row_mask:0xf bank_mask:0xf
	v_mov_b32_dpp v171, v139 row_shr:1 row_mask:0xf bank_mask:0xf
	v_cvt_pk_bf16_f32 v146, v146, v147
	v_cvt_pk_bf16_f32 v147, v148, v149
	v_pk_mul_f32 v[148:149], v[138:139], v[96:97]
	v_mov_b32_dpp v154, v138 row_shl:1 row_mask:0xf bank_mask:0xf
	v_mov_b32_dpp v155, v139 row_shl:1 row_mask:0xf bank_mask:0xf
	v_pk_fma_f32 v[148:149], v[88:89], v[170:171], v[148:149]
	v_pk_fma_f32 v[148:149], v[92:93], v[154:155], v[148:149]
	v_mul_f32_e32 v112, 0x3d372713, v148
	v_mul_f32_e32 v112, v148, v112
	v_mul_f32_e32 v152, 0x3d372713, v149
	v_fma_f32 v112, v148, v112, v148
	v_mul_f32_e32 v152, v149, v152
	v_mul_f32_e32 v112, 0xc0135761, v112
	v_fma_f32 v152, v149, v152, v149
	v_exp_f32_e32 v112, v112
	v_mul_f32_e32 v152, 0xc0135761, v152
	v_exp_f32_e32 v155, v152
	v_mov_b32_dpp v172, v156 row_ror:1 row_mask:0xf bank_mask:0xf
	v_add_f32_e32 v112, 1.0, v112
	v_rcp_f32_e32 v154, v112
	v_add_f32_e32 v112, 1.0, v155
	v_rcp_f32_e32 v155, v112
	v_mov_b32_dpp v173, v157 row_ror:1 row_mask:0xf bank_mask:0xf
	v_mov_b32_dpp v156, v120 row_ror:15 row_mask:0xf bank_mask:0xf
	v_mov_b32_dpp v172, v140 row_shr:1 row_mask:0xf bank_mask:0xf
	v_mov_b32_dpp v157, v121 row_ror:15 row_mask:0xf bank_mask:0xf
	v_mov_b32_dpp v173, v141 row_shr:1 row_mask:0xf bank_mask:0xf
	v_pk_mul_f32 v[158:159], v[140:141], v[98:99]
	v_mov_b32_dpp v156, v140 row_shl:1 row_mask:0xf bank_mask:0xf
	v_mov_b32_dpp v157, v141 row_shl:1 row_mask:0xf bank_mask:0xf
	v_pk_mul_f32 v[148:149], v[148:149], v[154:155]
	v_pk_fma_f32 v[154:155], v[90:91], v[172:173], v[158:159]
	v_pk_fma_f32 v[154:155], v[94:95], v[156:157], v[154:155]
	v_mul_f32_e32 v112, 0x3d372713, v154
	v_mul_f32_e32 v112, v154, v112
	v_mul_f32_e32 v156, 0x3d372713, v155
	v_fma_f32 v112, v154, v112, v154
	v_mul_f32_e32 v156, v155, v156
	v_mul_f32_e32 v112, 0xc0135761, v112
	v_fma_f32 v156, v155, v156, v155
	v_exp_f32_e32 v112, v112
	v_mul_f32_e32 v156, 0xc0135761, v156
	v_exp_f32_e32 v156, v156
	v_mov_b32_dpp v182, v114 row_ror:15 row_mask:0xf bank_mask:0xf
	v_mov_b32_dpp v180, v130 row_shr:1 row_mask:0xf bank_mask:0xf
	v_mov_b32_dpp v183, v115 row_ror:15 row_mask:0xf bank_mask:0xf
	v_mov_b32_dpp v181, v131 row_shr:1 row_mask:0xf bank_mask:0xf
	v_pk_mul_f32 v[152:153], v[130:131], v[72:73]
	v_mov_b32_dpp v182, v130 row_shl:1 row_mask:0xf bank_mask:0xf
; #define LAS __attribute__((address_space(3)))
; __device__ __forceinline__ unsigned pk2(float lo, float hi) { f32x2 v = {lo, hi}; bf16x2_t b = __builtin_convertvector(v, bf16x2_t); return __builtin_bit_cast(unsigned, b); }
; __device__ __forceinline__ float gelu_tanh(float x) {
;     const float t = x + 0.044715f * x * x * x;
;     const float e = __builtin_amdgcn_exp2f(-2.f * 0.7978845608028654f * LOG2E * t);
;     return x * __builtin_amdgcn_rcpf(1.f + e);
; }
;     __device__ __forceinline__ void operator()(const f32x4 (&acc)[2][2][4][2], const Unit& u, int wr, int wc, int fr, int fq, LAS unsigned char* lds) const {
;     ...
;                 const int trow = 64 * blk + 16 * m + fr;
;                 float og[8], ov[8];
; #pragma unroll
;                 for (int bj = 0; bj < 2; ++bj)
; #pragma unroll
;                     for (int n = 0; n < 2; ++n) {
;                         f32x4 pv, nv;
;                         if (m == 0) pv = (blk > 0) ? *(const LAS f32x4*)(XB + (2 * blk - 1) * 256 + bj * 128 + chl + 4 * n) : (f32x4){0.f, 0.f, 0.f, 0.f};
;                         if (m == 3) nv = (blk < 3) ? *(const LAS f32x4*)(XB + (2 * blk + 2) * 256 + bj * 128 + chl + 4 * n) : (f32x4){0.f, 0.f, 0.f, 0.f};
; #pragma unroll
;                         for (int e = 0; e < 4; ++e) {
;                             const float cur = acc[ai][bj][m][n][e];
;                             const float upB = (m == 0) ? pv[e] : dppf(0.f, acc[ai][bj][m == 0 ? 0 : m - 1][n][e], 0);
;                             const float dnB = (m == 3) ? nv[e] : dppf(0.f, acc[ai][bj][m == 3 ? 3 : m + 1][n][e], 1);
;                             const float up = dppf(upB, cur, 2), dn = dppf(dnB, cur, 3);
;                             const int k = 4 * n + e;
;                             if (bj == 0) og[k] = wg[0][k] * up + wg[1][k] * cur + wg[2][k] * dn;
;                             else         ov[k] = wv[0][k] * up + wv[1][k] * cur + wv[2][k] * dn;
;                         }
;                     }
;                 u32x4 ow;
; #pragma unroll
;                 for (int e2 = 0; e2 < 4; ++e2) ow[e2] = pk2(gelu_tanh(og[2 * e2]) * ov[2 * e2], gelu_tanh(og[2 * e2 + 1]) * ov[2 * e2 + 1]);
;                 if (trow != 0 && trow != 255) *(u32x4*)(ACTp + (size_t)(u.pm * BM + trow) * DFF + ch) = ow;
	v_mov_b32_dpp v183, v131 row_shl:1 row_mask:0xf bank_mask:0xf
	v_pk_fma_f32 v[152:153], v[64:65], v[180:181], v[152:153]
	v_add_f32_e32 v112, 1.0, v112
	v_pk_fma_f32 v[152:153], v[68:69], v[182:183], v[152:153]
	v_pk_mul_f32 v[148:149], v[148:149], v[152:153]
	v_rcp_f32_e32 v152, v112
	v_add_f32_e32 v112, 1.0, v156
	v_rcp_f32_e32 v153, v112
	v_mov_b32_dpp v186, v116 row_ror:15 row_mask:0xf bank_mask:0xf
	v_mov_b32_dpp v184, v132 row_shr:1 row_mask:0xf bank_mask:0xf
	v_mov_b32_dpp v187, v117 row_ror:15 row_mask:0xf bank_mask:0xf
	v_mov_b32_dpp v185, v133 row_shr:1 row_mask:0xf bank_mask:0xf
	v_pk_mul_f32 v[150:151], v[132:133], v[74:75]
	v_mov_b32_dpp v186, v132 row_shl:1 row_mask:0xf bank_mask:0xf
	v_mov_b32_dpp v187, v133 row_shl:1 row_mask:0xf bank_mask:0xf
	v_pk_fma_f32 v[150:151], v[66:67], v[184:185], v[150:151]
	v_pk_mul_f32 v[152:153], v[154:155], v[152:153]
	v_pk_fma_f32 v[150:151], v[70:71], v[186:187], v[150:151]
	v_or_b32_e32 v112, 32, v244
	v_pk_mul_f32 v[150:151], v[152:153], v[150:151]
	v_add_u32_e32 v112, s56, v112
	v_cvt_pk_bf16_f32 v148, v148, v149
	v_cvt_pk_bf16_f32 v149, v150, v151
	v_mad_i64_i32 v[150:151], s[18:19], v112, s80, v[164:165]
	v_lshl_add_u64 v[150:151], v[150:151], 0, v[162:163]
	v_cndmask_b32_e64 v112, 0, 1, s[38:39]
	v_mov_b32_e32 v178, 0
	global_store_dwordx4 v[150:151], v[146:149], off
	v_cmp_ne_u32_e64 s[18:19], 1, v112
	s_andn2_b64 vcc, exec, s[38:39]
	v_mov_b32_e32 v146, 0
	v_mov_b32_e32 v147, 0
	v_mov_b32_e32 v148, 0
	v_mov_b32_e32 v149, 0
	s_cbranch_vccnz .LBB0_1178
	ds_read_b128 v[146:149], v246 offset:2048
.LBB0_1178:
	v_mov_b32_dpp v150, v142 row_ror:1 row_mask:0xf bank_mask:0xf
	v_mov_b32_dpp v151, v143 row_ror:1 row_mask:0xf bank_mask:0xf
	v_mov_b32_dpp v152, v144 row_ror:1 row_mask:0xf bank_mask:0xf
	v_mov_b32_dpp v153, v145 row_ror:1 row_mask:0xf bank_mask:0xf
	v_mov_b32_dpp v150, v122 row_shr:1 row_mask:0xf bank_mask:0xf
	s_waitcnt lgkmcnt(0)
	v_mov_b32_dpp v146, v122 row_shl:1 row_mask:0xf bank_mask:0xf
	v_mov_b32_dpp v151, v123 row_shr:1 row_mask:0xf bank_mask:0xf
	v_mov_b32_dpp v147, v123 row_shl:1 row_mask:0xf bank_mask:0xf
	v_mov_b32_dpp v152, v124 row_shr:1 row_mask:0xf bank_mask:0xf
	v_mov_b32_dpp v148, v124 row_shl:1 row_mask:0xf bank_mask:0xf
	v_mov_b32_dpp v153, v125 row_shr:1 row_mask:0xf bank_mask:0xf
	v_mov_b32_dpp v149, v125 row_shl:1 row_mask:0xf bank_mask:0xf
	s_and_b64 vcc, exec, s[18:19]
	v_mov_b32_e32 v179, 0
	v_mov_b32_e32 v180, 0
	v_mov_b32_e32 v181, 0
	s_cbranch_vccnz .LBB0_1180
	ds_read_b128 v[178:181], v246 offset:2064
.LBB0_1180:
	v_mov_b32_dpp v154, v138 row_ror:1 row_mask:0xf bank_mask:0xf
	v_mov_b32_dpp v155, v139 row_ror:1 row_mask:0xf bank_mask:0xf
	v_mov_b32_dpp v156, v140 row_ror:1 row_mask:0xf bank_mask:0xf
	v_mov_b32_dpp v157, v141 row_ror:1 row_mask:0xf bank_mask:0xf
	v_mov_b32_e32 v142, 0
	v_mov_b32_dpp v154, v118 row_shr:1 row_mask:0xf bank_mask:0xf
	s_waitcnt lgkmcnt(0)
	v_mov_b32_dpp v178, v118 row_shl:1 row_mask:0xf bank_mask:0xf
	v_mov_b32_dpp v155, v119 row_shr:1 row_mask:0xf bank_mask:0xf
	v_mov_b32_dpp v179, v119 row_shl:1 row_mask:0xf bank_mask:0xf
	v_mov_b32_dpp v156, v120 row_shr:1 row_mask:0xf bank_mask:0xf
	v_mov_b32_dpp v180, v120 row_shl:1 row_mask:0xf bank_mask:0xf
	v_mov_b32_dpp v157, v121 row_shr:1 row_mask:0xf bank_mask:0xf
	v_mov_b32_dpp v181, v121 row_shl:1 row_mask:0xf bank_mask:0xf
	s_and_b64 vcc, exec, s[18:19]
	v_mov_b32_e32 v138, 0
	v_mov_b32_e32 v139, 0
	v_mov_b32_e32 v140, 0
	v_mov_b32_e32 v141, 0
	s_cbranch_vccnz .LBB0_1182
	ds_read_b128 v[138:141], v246 offset:2560
.LBB0_1182:
	v_mov_b32_dpp v158, v134 row_ror:1 row_mask:0xf bank_mask:0xf
	v_mov_b32_dpp v159, v135 row_ror:1 row_mask:0xf bank_mask:0xf
	v_mov_b32_dpp v160, v136 row_ror:1 row_mask:0xf bank_mask:0xf
	v_mov_b32_dpp v161, v137 row_ror:1 row_mask:0xf bank_mask:0xf
	v_mov_b32_dpp v158, v126 row_shr:1 row_mask:0xf bank_mask:0xf
	s_waitcnt lgkmcnt(0)
	v_mov_b32_dpp v138, v126 row_shl:1 row_mask:0xf bank_mask:0xf
	v_mov_b32_dpp v159, v127 row_shr:1 row_mask:0xf bank_mask:0xf
	v_mov_b32_dpp v139, v127 row_shl:1 row_mask:0xf bank_mask:0xf
	v_mov_b32_dpp v160, v128 row_shr:1 row_mask:0xf bank_mask:0xf
	v_mov_b32_dpp v140, v128 row_shl:1 row_mask:0xf bank_mask:0xf
	v_mov_b32_dpp v161, v129 row_shr:1 row_mask:0xf bank_mask:0xf
	v_mov_b32_dpp v141, v129 row_shl:1 row_mask:0xf bank_mask:0xf
	s_and_b64 vcc, exec, s[18:19]
	v_mov_b32_e32 v143, 0
	v_mov_b32_e32 v144, 0
	v_mov_b32_e32 v145, 0
	s_cbranch_vccnz .LBB0_1184
	ds_read_b128 v[142:145], v246 offset:2576
; #define LAS __attribute__((address_space(3)))
; __device__ __forceinline__ unsigned pk2(float lo, float hi) { f32x2 v = {lo, hi}; bf16x2_t b = __builtin_convertvector(v, bf16x2_t); return __builtin_bit_cast(unsigned, b); }
; __device__ __forceinline__ float gelu_tanh(float x) {
;     const float t = x + 0.044715f * x * x * x;
;     const float e = __builtin_amdgcn_exp2f(-2.f * 0.7978845608028654f * LOG2E * t);
;     return x * __builtin_amdgcn_rcpf(1.f + e);
; }
;     __device__ __forceinline__ void operator()(const f32x4 (&acc)[2][2][4][2], const Unit& u, int wr, int wc, int fr, int fq, LAS unsigned char* lds) const {
;     ...
;                 const int trow = 64 * blk + 16 * m + fr;
;                 float og[8], ov[8];
; #pragma unroll
;                 for (int bj = 0; bj < 2; ++bj)
; #pragma unroll
;                     for (int n = 0; n < 2; ++n) {
;                         f32x4 pv, nv;
;                         if (m == 0) pv = (blk > 0) ? *(const LAS f32x4*)(XB + (2 * blk - 1) * 256 + bj * 128 + chl + 4 * n) : (f32x4){0.f, 0.f, 0.f, 0.f};
;                         if (m == 3) nv = (blk < 3) ? *(const LAS f32x4*)(XB + (2 * blk + 2) * 256 + bj * 128 + chl + 4 * n) : (f32x4){0.f, 0.f, 0.f, 0.f};
; #pragma unroll
;                         for (int e = 0; e < 4; ++e) {
;                             const float cur = acc[ai][bj][m][n][e];
;                             const float upB = (m == 0) ? pv[e] : dppf(0.f, acc[ai][bj][m == 0 ? 0 : m - 1][n][e], 0);
;                             const float dnB = (m == 3) ? nv[e] : dppf(0.f, acc[ai][bj][m == 3 ? 3 : m + 1][n][e], 1);
;                             const float up = dppf(upB, cur, 2), dn = dppf(dnB, cur, 3);
;                             const int k = 4 * n + e;
;                             if (bj == 0) og[k] = wg[0][k] * up + wg[1][k] * cur + wg[2][k] * dn;
;                             else         ov[k] = wv[0][k] * up + wv[1][k] * cur + wv[2][k] * dn;
;                         }
;                     }
;                 u32x4 ow;
; #pragma unroll
;                 for (int e2 = 0; e2 < 4; ++e2) ow[e2] = pk2(gelu_tanh(og[2 * e2]) * ov[2 * e2], gelu_tanh(og[2 * e2 + 1]) * ov[2 * e2 + 1]);
;                 if (trow != 0 && trow != 255) *(u32x4*)(ACTp + (size_t)(u.pm * BM + trow) * DFF + ch) = ow;
.LBB0_1184:
	s_waitcnt lgkmcnt(0)
	v_mov_b32_dpp v142, v114 row_shl:1 row_mask:0xf bank_mask:0xf
	v_mov_b32_dpp v134, v130 row_ror:1 row_mask:0xf bank_mask:0xf
	v_mov_b32_dpp v135, v131 row_ror:1 row_mask:0xf bank_mask:0xf
	v_mov_b32_dpp v134, v114 row_shr:1 row_mask:0xf bank_mask:0xf
	v_mov_b32_dpp v130, v132 row_ror:1 row_mask:0xf bank_mask:0xf
	v_mov_b32_dpp v131, v133 row_ror:1 row_mask:0xf bank_mask:0xf
	v_mov_b32_dpp v135, v115 row_shr:1 row_mask:0xf bank_mask:0xf
	v_mov_b32_dpp v143, v115 row_shl:1 row_mask:0xf bank_mask:0xf
	v_mov_b32_dpp v130, v116 row_shr:1 row_mask:0xf bank_mask:0xf
	v_mov_b32_dpp v144, v116 row_shl:1 row_mask:0xf bank_mask:0xf
	v_mov_b32_dpp v131, v117 row_shr:1 row_mask:0xf bank_mask:0xf
	v_mov_b32_dpp v145, v117 row_shl:1 row_mask:0xf bank_mask:0xf
	s_and_saveexec_b64 s[18:19], s[10:11]
	s_cbranch_execz .LBB0_1186
	v_pk_mul_f32 v[122:123], v[122:123], v[84:85]
	v_pk_mul_f32 v[132:133], v[116:117], v[74:75]
	v_pk_fma_f32 v[122:123], v[76:77], v[150:151], v[122:123]
	v_pk_mul_f32 v[124:125], v[124:125], v[86:87]
	v_pk_fma_f32 v[122:123], v[80:81], v[146:147], v[122:123]
	v_pk_fma_f32 v[124:125], v[78:79], v[152:153], v[124:125]
	v_mul_f32_e32 v112, 0x3d372713, v122
	v_mul_f32_e32 v112, v122, v112
	v_mul_f32_e32 v116, 0x3d372713, v123
	v_fma_f32 v112, v122, v112, v122
	v_mul_f32_e32 v116, v123, v116
	v_mul_f32_e32 v112, 0xc0135761, v112
	v_fma_f32 v116, v123, v116, v123
	v_pk_fma_f32 v[124:125], v[82:83], v[148:149], v[124:125]
	v_exp_f32_e32 v112, v112
	v_mul_f32_e32 v116, 0xc0135761, v116
	v_exp_f32_e32 v136, v116
	v_pk_mul_f32 v[116:117], v[114:115], v[72:73]
	v_mul_f32_e32 v115, 0x3d372713, v124
	v_mul_f32_e32 v115, v124, v115
	v_fma_f32 v115, v124, v115, v124
	v_add_f32_e32 v112, 1.0, v112
	v_mul_f32_e32 v115, 0xc0135761, v115
	v_rcp_f32_e32 v114, v112
	v_add_f32_e32 v112, 1.0, v136
	v_exp_f32_e32 v136, v115
	v_mul_f32_e32 v115, 0x3d372713, v125
	v_mul_f32_e32 v115, v125, v115
	v_fma_f32 v115, v125, v115, v125
	v_mul_f32_e32 v115, 0xc0135761, v115
	v_exp_f32_e32 v137, v115
	v_rcp_f32_e32 v115, v112
	v_pk_mul_f32 v[126:127], v[126:127], v[108:109]
	v_pk_mul_f32 v[118:119], v[118:119], v[96:97]
	v_pk_fma_f32 v[126:127], v[100:101], v[158:159], v[126:127]
	v_pk_fma_f32 v[118:119], v[88:89], v[154:155], v[118:119]
	v_add_f32_e32 v112, 1.0, v136
	v_pk_fma_f32 v[126:127], v[104:105], v[138:139], v[126:127]
	v_pk_fma_f32 v[118:119], v[92:93], v[178:179], v[118:119]
	v_rcp_f32_e32 v136, v112
	v_add_f32_e32 v112, 1.0, v137
	v_pk_mul_f32 v[114:115], v[122:123], v[114:115]
	v_rcp_f32_e32 v137, v112
	v_pk_mul_f32 v[114:115], v[114:115], v[126:127]
	v_mul_f32_e32 v112, 0x3d372713, v118
	v_cvt_pk_bf16_f32 v114, v114, v115
	v_mul_f32_e32 v112, v118, v112
	v_mul_f32_e32 v115, 0x3d372713, v119
	v_fma_f32 v112, v118, v112, v118
	v_mul_f32_e32 v115, v119, v115
	v_mul_f32_e32 v112, 0xc0135761, v112
	v_fma_f32 v115, v119, v115, v119
	v_exp_f32_e32 v112, v112
	v_mul_f32_e32 v115, 0xc0135761, v115
	v_exp_f32_e32 v115, v115
	v_pk_mul_f32 v[128:129], v[128:129], v[110:111]
	v_pk_mul_f32 v[120:121], v[120:121], v[98:99]
	v_pk_fma_f32 v[128:129], v[102:103], v[160:161], v[128:129]
	v_pk_fma_f32 v[120:121], v[90:91], v[156:157], v[120:121]
	v_add_f32_e32 v112, 1.0, v112
	v_pk_fma_f32 v[128:129], v[106:107], v[140:141], v[128:129]
	v_pk_fma_f32 v[120:121], v[94:95], v[180:181], v[120:121]
	v_pk_mul_f32 v[122:123], v[124:125], v[136:137]
	v_rcp_f32_e32 v124, v112
	v_add_f32_e32 v112, 1.0, v115
	v_pk_mul_f32 v[122:123], v[122:123], v[128:129]
	v_rcp_f32_e32 v125, v112
	v_mul_f32_e32 v112, 0x3d372713, v120
	v_cvt_pk_bf16_f32 v115, v122, v123
	v_mul_f32_e32 v112, v120, v112
	v_mul_f32_e32 v122, 0x3d372713, v121
	v_fma_f32 v112, v120, v112, v120
	v_mul_f32_e32 v122, v121, v122
	v_mul_f32_e32 v112, 0xc0135761, v112
	v_fma_f32 v122, v121, v122, v121
	v_exp_f32_e32 v112, v112
	v_mul_f32_e32 v122, 0xc0135761, v122
	v_exp_f32_e32 v122, v122
	v_pk_fma_f32 v[116:117], v[64:65], v[134:135], v[116:117]
	v_pk_mul_f32 v[118:119], v[118:119], v[124:125]
	v_pk_fma_f32 v[116:117], v[68:69], v[142:143], v[116:117]
	v_add_f32_e32 v112, 1.0, v112
	v_pk_mul_f32 v[116:117], v[118:119], v[116:117]
	v_rcp_f32_e32 v118, v112
	v_add_f32_e32 v112, 1.0, v122
	v_rcp_f32_e32 v119, v112
	v_pk_fma_f32 v[122:123], v[66:67], v[130:131], v[132:133]
	v_or_b32_e32 v112, 48, v244
	v_pk_fma_f32 v[122:123], v[70:71], v[144:145], v[122:123]
	v_pk_mul_f32 v[118:119], v[120:121], v[118:119]
	v_cvt_pk_bf16_f32 v116, v116, v117
	v_pk_mul_f32 v[118:119], v[118:119], v[122:123]
	v_add_u32_e32 v112, s56, v112
	v_cvt_pk_bf16_f32 v117, v118, v119
	v_mov_b64_e32 v[118:119], s[88:89]
	v_mad_i64_i32 v[118:119], s[54:55], v112, s80, v[118:119]
	v_lshl_add_u64 v[118:119], v[216:217], 1, v[118:119]
	global_store_dwordx4 v[118:119], v[114:117], off

; #define LAS __attribute__((address_space(3)))
; __device__ __forceinline__ unsigned pk2(float lo, float hi) { f32x2 v = {lo, hi}; bf16x2_t b = __builtin_convertvector(v, bf16x2_t); return __builtin_bit_cast(unsigned, b); }
; __device__ __forceinline__ float gelu_tanh(float x) {
;     const float t = x + 0.044715f * x * x * x;
;     const float e = __builtin_amdgcn_exp2f(-2.f * 0.7978845608028654f * LOG2E * t);
;     return x * __builtin_amdgcn_rcpf(1.f + e);
; }
;     __device__ __forceinline__ void operator()(const f32x4 (&acc)[2][2][4][2], const Unit& u, int wr, int wc, int fr, int fq, LAS unsigned char* lds) const {
;     ...
;                 const int trow = 64 * blk + 16 * m + fr;
;                 float og[8], ov[8];
; #pragma unroll
;                 for (int bj = 0; bj < 2; ++bj)
; #pragma unroll
;                     for (int n = 0; n < 2; ++n) {
;                         f32x4 pv, nv;
;                         if (m == 0) pv = (blk > 0) ? *(const LAS f32x4*)(XB + (2 * blk - 1) * 256 + bj * 128 + chl + 4 * n) : (f32x4){0.f, 0.f, 0.f, 0.f};
;                         if (m == 3) nv = (blk < 3) ? *(const LAS f32x4*)(XB + (2 * blk + 2) * 256 + bj * 128 + chl + 4 * n) : (f32x4){0.f, 0.f, 0.f, 0.f};
; #pragma unroll
;                         for (int e = 0; e < 4; ++e) {
;                             const float cur = acc[ai][bj][m][n][e];
;                             const float upB = (m == 0) ? pv[e] : dppf(0.f, acc[ai][bj][m == 0 ? 0 : m - 1][n][e], 0);
;                             const float dnB = (m == 3) ? nv[e] : dppf(0.f, acc[ai][bj][m == 3 ? 3 : m + 1][n][e], 1);
;                             const float up = dppf(upB, cur, 2), dn = dppf(dnB, cur, 3);
;                             const int k = 4 * n + e;
;                             if (bj == 0) og[k] = wg[0][k] * up + wg[1][k] * cur + wg[2][k] * dn;
;                             else         ov[k] = wv[0][k] * up + wv[1][k] * cur + wv[2][k] * dn;
;                         }
;                     }
;                 u32x4 ow;
; #pragma unroll
;                 for (int e2 = 0; e2 < 4; ++e2) ow[e2] = pk2(gelu_tanh(og[2 * e2]) * ov[2 * e2], gelu_tanh(og[2 * e2 + 1]) * ov[2 * e2 + 1]);
;                 if (trow != 0 && trow != 255) *(u32x4*)(ACTp + (size_t)(u.pm * BM + trow) * DFF + ch) = ow;
.LBB0_1188:
	v_mov_b32_dpp v130, v44 row_ror:15 row_mask:0xf bank_mask:0xf
	v_mov_b32_dpp v131, v45 row_ror:15 row_mask:0xf bank_mask:0xf
	v_mov_b32_dpp v132, v46 row_ror:15 row_mask:0xf bank_mask:0xf
	v_mov_b32_dpp v133, v47 row_ror:15 row_mask:0xf bank_mask:0xf
	s_waitcnt lgkmcnt(0)
	v_mov_b32_dpp v118, v60 row_shr:1 row_mask:0xf bank_mask:0xf
	v_mov_b32_dpp v130, v60 row_shl:1 row_mask:0xf bank_mask:0xf
	v_mov_b32_dpp v119, v61 row_shr:1 row_mask:0xf bank_mask:0xf
	v_mov_b32_dpp v131, v61 row_shl:1 row_mask:0xf bank_mask:0xf
	v_mov_b32_dpp v120, v62 row_shr:1 row_mask:0xf bank_mask:0xf
	v_mov_b32_dpp v132, v62 row_shl:1 row_mask:0xf bank_mask:0xf
	v_mov_b32_dpp v121, v63 row_shr:1 row_mask:0xf bank_mask:0xf
	v_mov_b32_dpp v133, v63 row_shl:1 row_mask:0xf bank_mask:0xf
	s_and_b64 vcc, exec, s[18:19]
	v_mov_b32_e32 v123, 0
	v_mov_b32_e32 v124, 0
	v_mov_b32_e32 v125, 0
	s_cbranch_vccnz .LBB0_1190
	ds_read_b128 v[122:125], v254 offset:16
.LBB0_1190:
	v_mov_b32_dpp v138, v40 row_ror:15 row_mask:0xf bank_mask:0xf
	v_mov_b32_dpp v139, v41 row_ror:15 row_mask:0xf bank_mask:0xf
	v_mov_b32_dpp v140, v42 row_ror:15 row_mask:0xf bank_mask:0xf
	v_mov_b32_dpp v141, v43 row_ror:15 row_mask:0xf bank_mask:0xf
	v_mov_b32_e32 v114, 0
	s_waitcnt lgkmcnt(0)
	v_mov_b32_dpp v122, v52 row_shr:1 row_mask:0xf bank_mask:0xf
	v_mov_b32_dpp v138, v52 row_shl:1 row_mask:0xf bank_mask:0xf
	v_mov_b32_dpp v123, v53 row_shr:1 row_mask:0xf bank_mask:0xf
	v_mov_b32_dpp v139, v53 row_shl:1 row_mask:0xf bank_mask:0xf
	v_mov_b32_dpp v124, v54 row_shr:1 row_mask:0xf bank_mask:0xf
	v_mov_b32_dpp v140, v54 row_shl:1 row_mask:0xf bank_mask:0xf
	v_mov_b32_dpp v125, v55 row_shr:1 row_mask:0xf bank_mask:0xf
	v_mov_b32_dpp v141, v55 row_shl:1 row_mask:0xf bank_mask:0xf
	s_and_b64 vcc, exec, s[18:19]
	v_mov_b32_e32 v126, 0
	v_mov_b32_e32 v127, 0
	v_mov_b32_e32 v128, 0
	v_mov_b32_e32 v129, 0
	s_cbranch_vccnz .LBB0_1192
	ds_read_b128 v[126:129], v254 offset:512
.LBB0_1192:
	v_mov_b32_dpp v142, v36 row_ror:15 row_mask:0xf bank_mask:0xf
	v_mov_b32_dpp v143, v37 row_ror:15 row_mask:0xf bank_mask:0xf
	v_mov_b32_dpp v144, v38 row_ror:15 row_mask:0xf bank_mask:0xf
	v_mov_b32_dpp v145, v39 row_ror:15 row_mask:0xf bank_mask:0xf
	s_waitcnt lgkmcnt(0)
	v_mov_b32_dpp v126, v56 row_shr:1 row_mask:0xf bank_mask:0xf
	v_mov_b32_dpp v142, v56 row_shl:1 row_mask:0xf bank_mask:0xf
	v_mov_b32_dpp v127, v57 row_shr:1 row_mask:0xf bank_mask:0xf
	v_mov_b32_dpp v143, v57 row_shl:1 row_mask:0xf bank_mask:0xf
	v_mov_b32_dpp v128, v58 row_shr:1 row_mask:0xf bank_mask:0xf
	v_mov_b32_dpp v144, v58 row_shl:1 row_mask:0xf bank_mask:0xf
	v_mov_b32_dpp v129, v59 row_shr:1 row_mask:0xf bank_mask:0xf
	v_mov_b32_dpp v145, v59 row_shl:1 row_mask:0xf bank_mask:0xf
	s_and_b64 vcc, exec, s[18:19]
	v_mov_b32_e32 v115, 0
	v_mov_b32_e32 v116, 0
	v_mov_b32_e32 v117, 0
	s_cbranch_vccnz .LBB0_1194
	ds_read_b128 v[114:117], v254 offset:528
.LBB0_1194:
	v_mov_b32_dpp v136, v32 row_ror:15 row_mask:0xf bank_mask:0xf
	v_mov_b32_dpp v137, v33 row_ror:15 row_mask:0xf bank_mask:0xf
	v_mov_b32_dpp v134, v34 row_ror:15 row_mask:0xf bank_mask:0xf
	v_mov_b32_dpp v135, v35 row_ror:15 row_mask:0xf bank_mask:0xf
	s_waitcnt lgkmcnt(0)
	v_mov_b32_dpp v114, v48 row_shr:1 row_mask:0xf bank_mask:0xf
	v_mov_b32_dpp v136, v48 row_shl:1 row_mask:0xf bank_mask:0xf
	v_mov_b32_dpp v115, v49 row_shr:1 row_mask:0xf bank_mask:0xf
	v_mov_b32_dpp v137, v49 row_shl:1 row_mask:0xf bank_mask:0xf
	v_mov_b32_dpp v116, v50 row_shr:1 row_mask:0xf bank_mask:0xf
	v_mov_b32_dpp v134, v50 row_shl:1 row_mask:0xf bank_mask:0xf
	v_mov_b32_dpp v117, v51 row_shr:1 row_mask:0xf bank_mask:0xf
	v_mov_b32_dpp v135, v51 row_shl:1 row_mask:0xf bank_mask:0xf
	s_and_saveexec_b64 s[18:19], s[12:13]
	s_cbranch_execz .LBB0_1196
	v_pk_mul_f32 v[148:149], v[56:57], v[108:109]
	v_pk_mul_f32 v[146:147], v[58:59], v[110:111]
	v_pk_fma_f32 v[126:127], v[100:101], v[126:127], v[148:149]
	v_pk_fma_f32 v[128:129], v[102:103], v[128:129], v[146:147]
	v_pk_fma_f32 v[126:127], v[104:105], v[142:143], v[126:127]
	v_pk_mul_f32 v[142:143], v[54:55], v[98:99]
	v_pk_fma_f32 v[128:129], v[106:107], v[144:145], v[128:129]
	v_pk_fma_f32 v[124:125], v[90:91], v[124:125], v[142:143]
	v_pk_mul_f32 v[144:145], v[52:53], v[96:97]
	v_pk_fma_f32 v[124:125], v[94:95], v[140:141], v[124:125]
	v_pk_mul_f32 v[140:141], v[60:61], v[84:85]
	v_pk_fma_f32 v[122:123], v[88:89], v[122:123], v[144:145]
	v_pk_fma_f32 v[118:119], v[76:77], v[118:119], v[140:141]
	v_pk_fma_f32 v[122:123], v[92:93], v[138:139], v[122:123]
	v_pk_mul_f32 v[138:139], v[62:63], v[86:87]
	v_pk_fma_f32 v[118:119], v[80:81], v[130:131], v[118:119]
	v_pk_fma_f32 v[120:121], v[78:79], v[120:121], v[138:139]
	v_mul_f32_e32 v112, 0x3d372713, v118
	v_pk_fma_f32 v[120:121], v[82:83], v[132:133], v[120:121]
	v_mul_f32_e32 v112, v118, v112
	v_mul_f32_e32 v132, 0x3d372713, v119
	v_fma_f32 v112, v118, v112, v118
	v_mul_f32_e32 v132, v119, v132
	v_mul_f32_e32 v112, 0xc0135761, v112
	v_fma_f32 v132, v119, v132, v119
	v_exp_f32_e32 v112, v112
	v_mul_f32_e32 v132, 0xc0135761, v132
	v_exp_f32_e32 v139, v132
	v_pk_mul_f32 v[132:133], v[48:49], v[72:73]
	v_add_f32_e32 v112, 1.0, v112
	v_rcp_f32_e32 v138, v112
	v_add_f32_e32 v112, 1.0, v139
	v_mul_f32_e32 v139, 0x3d372713, v120
	v_mul_f32_e32 v139, v120, v139
	v_fma_f32 v139, v120, v139, v120
	v_mul_f32_e32 v139, 0xc0135761, v139
	v_exp_f32_e32 v140, v139
	v_mul_f32_e32 v139, 0x3d372713, v121
	v_mul_f32_e32 v139, v121, v139
	v_fma_f32 v139, v121, v139, v121
	v_mul_f32_e32 v139, 0xc0135761, v139
	v_exp_f32_e32 v141, v139
	v_rcp_f32_e32 v139, v112
	v_add_f32_e32 v112, 1.0, v140
	v_rcp_f32_e32 v140, v112
; #define LAS __attribute__((address_space(3)))
; __device__ __forceinline__ unsigned pk2(float lo, float hi) { f32x2 v = {lo, hi}; bf16x2_t b = __builtin_convertvector(v, bf16x2_t); return __builtin_bit_cast(unsigned, b); }
; __device__ __forceinline__ float gelu_tanh(float x) {
;     const float t = x + 0.044715f * x * x * x;
;     const float e = __builtin_amdgcn_exp2f(-2.f * 0.7978845608028654f * LOG2E * t);
;     return x * __builtin_amdgcn_rcpf(1.f + e);
; }
;     __device__ __forceinline__ void operator()(const f32x4 (&acc)[2][2][4][2], const Unit& u, int wr, int wc, int fr, int fq, LAS unsigned char* lds) const {
;     ...
;                 const int trow = 64 * blk + 16 * m + fr;
;                 float og[8], ov[8];
; #pragma unroll
;                 for (int bj = 0; bj < 2; ++bj)
; #pragma unroll
;                     for (int n = 0; n < 2; ++n) {
;                         f32x4 pv, nv;
;                         if (m == 0) pv = (blk > 0) ? *(const LAS f32x4*)(XB + (2 * blk - 1) * 256 + bj * 128 + chl + 4 * n) : (f32x4){0.f, 0.f, 0.f, 0.f};
;                         if (m == 3) nv = (blk < 3) ? *(const LAS f32x4*)(XB + (2 * blk + 2) * 256 + bj * 128 + chl + 4 * n) : (f32x4){0.f, 0.f, 0.f, 0.f};
; #pragma unroll
;                         for (int e = 0; e < 4; ++e) {
;                             const float cur = acc[ai][bj][m][n][e];
;                             const float upB = (m == 0) ? pv[e] : dppf(0.f, acc[ai][bj][m == 0 ? 0 : m - 1][n][e], 0);
;                             const float dnB = (m == 3) ? nv[e] : dppf(0.f, acc[ai][bj][m == 3 ? 3 : m + 1][n][e], 1);
;                             const float up = dppf(upB, cur, 2), dn = dppf(dnB, cur, 3);
;                             const int k = 4 * n + e;
;                             if (bj == 0) og[k] = wg[0][k] * up + wg[1][k] * cur + wg[2][k] * dn;
;                             else         ov[k] = wv[0][k] * up + wv[1][k] * cur + wv[2][k] * dn;
;                         }
;                     }
;                 u32x4 ow;
; #pragma unroll
;                 for (int e2 = 0; e2 < 4; ++e2) ow[e2] = pk2(gelu_tanh(og[2 * e2]) * ov[2 * e2], gelu_tanh(og[2 * e2 + 1]) * ov[2 * e2 + 1]);
;                 if (trow != 0 && trow != 255) *(u32x4*)(ACTp + (size_t)(u.pm * BM + trow) * DFF + ch) = ow;
	v_add_f32_e32 v112, 1.0, v141
	v_pk_mul_f32 v[118:119], v[118:119], v[138:139]
	v_rcp_f32_e32 v141, v112
	v_pk_mul_f32 v[118:119], v[118:119], v[126:127]
	v_mul_f32_e32 v112, 0x3d372713, v122
	v_cvt_pk_bf16_f32 v118, v118, v119
	v_mul_f32_e32 v112, v122, v112
	v_mul_f32_e32 v119, 0x3d372713, v123
	v_fma_f32 v112, v122, v112, v122
	v_mul_f32_e32 v119, v123, v119
	v_mul_f32_e32 v112, 0xc0135761, v112
	v_fma_f32 v119, v123, v119, v123
	v_exp_f32_e32 v112, v112
	v_mul_f32_e32 v119, 0xc0135761, v119
	v_exp_f32_e32 v119, v119
	v_pk_mul_f32 v[120:121], v[120:121], v[140:141]
	v_add_f32_e32 v112, 1.0, v112
	v_rcp_f32_e32 v126, v112
	v_add_f32_e32 v112, 1.0, v119
	v_rcp_f32_e32 v127, v112
	v_pk_mul_f32 v[120:121], v[120:121], v[128:129]
	v_mul_f32_e32 v112, 0x3d372713, v124
	v_cvt_pk_bf16_f32 v119, v120, v121
	v_pk_mul_f32 v[120:121], v[122:123], v[126:127]
	v_mul_f32_e32 v112, v124, v112
	v_mul_f32_e32 v122, 0x3d372713, v125
	v_fma_f32 v112, v124, v112, v124
	v_mul_f32_e32 v122, v125, v122
	v_mul_f32_e32 v112, 0xc0135761, v112
	v_fma_f32 v122, v125, v122, v125
	v_exp_f32_e32 v112, v112
	v_mul_f32_e32 v122, 0xc0135761, v122
	v_exp_f32_e32 v123, v122
	v_pk_fma_f32 v[114:115], v[64:65], v[114:115], v[132:133]
	v_add_f32_e32 v112, 1.0, v112
	v_rcp_f32_e32 v122, v112
	v_add_f32_e32 v112, 1.0, v123
	v_rcp_f32_e32 v123, v112
	v_pk_fma_f32 v[114:115], v[68:69], v[136:137], v[114:115]
	v_pk_mul_f32 v[130:131], v[50:51], v[74:75]
	v_pk_mul_f32 v[114:115], v[120:121], v[114:115]
	v_add_u32_e32 v112, s56, v253
	v_cvt_pk_bf16_f32 v120, v114, v115
	v_pk_fma_f32 v[114:115], v[66:67], v[116:117], v[130:131]
	v_pk_mul_f32 v[116:117], v[124:125], v[122:123]
	v_pk_fma_f32 v[114:115], v[70:71], v[134:135], v[114:115]
	s_nop 0
	v_pk_mul_f32 v[114:115], v[116:117], v[114:115]
	s_nop 0
	v_cvt_pk_bf16_f32 v121, v114, v115
	v_mov_b64_e32 v[114:115], s[88:89]
	v_mad_i64_i32 v[114:115], s[54:55], v112, s80, v[114:115]
	v_lshl_add_u64 v[114:115], v[216:217], 1, v[114:115]
	global_store_dwordx4 v[114:115], v[118:121], off
.LBB0_1196:
	s_or_b64 exec, exec, s[18:19]
	v_mov_b32_dpp v116, v60 row_ror:1 row_mask:0xf bank_mask:0xf
	v_mov_b32_dpp v117, v61 row_ror:1 row_mask:0xf bank_mask:0xf
	v_mov_b32_dpp v60, v28 row_ror:15 row_mask:0xf bank_mask:0xf
	v_mov_b32_dpp v116, v44 row_shr:1 row_mask:0xf bank_mask:0xf
	v_mov_b32_dpp v61, v29 row_ror:15 row_mask:0xf bank_mask:0xf
	v_mov_b32_dpp v117, v45 row_shr:1 row_mask:0xf bank_mask:0xf
	v_mov_b32_dpp v130, v50 row_ror:1 row_mask:0xf bank_mask:0xf
	v_mov_b32_dpp v131, v51 row_ror:1 row_mask:0xf bank_mask:0xf
	v_pk_mul_f32 v[50:51], v[44:45], v[84:85]
	v_mov_b32_dpp v60, v44 row_shl:1 row_mask:0xf bank_mask:0xf
	v_mov_b32_dpp v61, v45 row_shl:1 row_mask:0xf bank_mask:0xf
	v_pk_fma_f32 v[50:51], v[76:77], v[116:117], v[50:51]
	v_pk_fma_f32 v[50:51], v[80:81], v[60:61], v[50:51]
	v_mul_f32_e32 v60, 0x3d372713, v50
	v_mul_f32_e32 v60, v50, v60
	v_fma_f32 v60, v50, v60, v50
	v_mul_f32_e32 v60, 0xc0135761, v60
	v_exp_f32_e32 v112, v60
	v_mul_f32_e32 v60, 0x3d372713, v51
	v_mul_f32_e32 v60, v51, v60
	v_fma_f32 v60, v51, v60, v51
	v_mov_b32_dpp v124, v56 row_ror:1 row_mask:0xf bank_mask:0xf
	v_mov_b32_dpp v125, v57 row_ror:1 row_mask:0xf bank_mask:0xf
	v_mul_f32_e32 v60, 0xc0135761, v60
	v_mov_b32_dpp v56, v20 row_ror:15 row_mask:0xf bank_mask:0xf
	v_mov_b32_dpp v124, v36 row_shr:1 row_mask:0xf bank_mask:0xf
	v_mov_b32_dpp v57, v21 row_ror:15 row_mask:0xf bank_mask:0xf
	v_mov_b32_dpp v125, v37 row_shr:1 row_mask:0xf bank_mask:0xf
	v_exp_f32_e32 v115, v60
	v_pk_mul_f32 v[60:61], v[36:37], v[108:109]
	v_mov_b32_dpp v118, v62 row_ror:1 row_mask:0xf bank_mask:0xf
	v_mov_b32_dpp v119, v63 row_ror:1 row_mask:0xf bank_mask:0xf
	v_mov_b32_dpp v56, v36 row_shl:1 row_mask:0xf bank_mask:0xf
	v_mov_b32_dpp v57, v37 row_shl:1 row_mask:0xf bank_mask:0xf
	v_pk_fma_f32 v[60:61], v[100:101], v[124:125], v[60:61]
	v_mov_b32_dpp v62, v30 row_ror:15 row_mask:0xf bank_mask:0xf
	v_mov_b32_dpp v118, v46 row_shr:1 row_mask:0xf bank_mask:0xf
	v_mov_b32_dpp v63, v31 row_ror:15 row_mask:0xf bank_mask:0xf
	v_mov_b32_dpp v119, v47 row_shr:1 row_mask:0xf bank_mask:0xf
	v_pk_fma_f32 v[56:57], v[104:105], v[56:57], v[60:61]
	v_pk_mul_f32 v[60:61], v[46:47], v[86:87]
	v_mov_b32_dpp v62, v46 row_shl:1 row_mask:0xf bank_mask:0xf
	v_mov_b32_dpp v63, v47 row_shl:1 row_mask:0xf bank_mask:0xf
	v_pk_fma_f32 v[60:61], v[78:79], v[118:119], v[60:61]
	v_add_f32_e32 v112, 1.0, v112
	v_pk_fma_f32 v[60:61], v[82:83], v[62:63], v[60:61]
	v_rcp_f32_e32 v116, v112
	v_mul_f32_e32 v62, 0x3d372713, v60
	v_mul_f32_e32 v63, 0x3d372713, v61
	v_mul_f32_e32 v62, v60, v62
	v_mul_f32_e32 v63, v61, v63
	v_add_f32_e32 v112, 1.0, v115
	v_fma_f32 v62, v60, v62, v60
	v_fma_f32 v63, v61, v63, v61
	v_rcp_f32_e32 v117, v112
	v_mul_f32_e32 v62, 0xc0135761, v62
	v_mul_f32_e32 v63, 0xc0135761, v63
	v_exp_f32_e32 v62, v62
	v_exp_f32_e32 v63, v63
	v_pk_mul_f32 v[50:51], v[50:51], v[116:117]
	v_pk_mul_f32 v[50:51], v[50:51], v[56:57]
	v_add_f32_e32 v56, 1.0, v62
	v_add_f32_e32 v57, 1.0, v63
	v_rcp_f32_e32 v56, v56
	v_rcp_f32_e32 v57, v57
	v_mov_b32_dpp v126, v58 row_ror:1 row_mask:0xf bank_mask:0xf
	v_mov_b32_dpp v127, v59 row_ror:1 row_mask:0xf bank_mask:0xf
	v_mov_b32_dpp v58, v22 row_ror:15 row_mask:0xf bank_mask:0xf
	v_mov_b32_dpp v126, v38 row_shr:1 row_mask:0xf bank_mask:0xf
	v_mov_b32_dpp v59, v23 row_ror:15 row_mask:0xf bank_mask:0xf
	v_mov_b32_dpp v127, v39 row_shr:1 row_mask:0xf bank_mask:0xf
	v_pk_mul_f32 v[134:135], v[38:39], v[110:111]
	v_mov_b32_dpp v58, v38 row_shl:1 row_mask:0xf bank_mask:0xf
	v_mov_b32_dpp v59, v39 row_shl:1 row_mask:0xf bank_mask:0xf
	v_pk_fma_f32 v[62:63], v[102:103], v[126:127], v[134:135]
; #define LAS __attribute__((address_space(3)))
; __device__ __forceinline__ unsigned pk2(float lo, float hi) { f32x2 v = {lo, hi}; bf16x2_t b = __builtin_convertvector(v, bf16x2_t); return __builtin_bit_cast(unsigned, b); }
; __device__ __forceinline__ float gelu_tanh(float x) {
;     const float t = x + 0.044715f * x * x * x;
;     const float e = __builtin_amdgcn_exp2f(-2.f * 0.7978845608028654f * LOG2E * t);
;     return x * __builtin_amdgcn_rcpf(1.f + e);
; }
;     __device__ __forceinline__ void operator()(const f32x4 (&acc)[2][2][4][2], const Unit& u, int wr, int wc, int fr, int fq, LAS unsigned char* lds) const {
;     ...
;                 const int trow = 64 * blk + 16 * m + fr;
;                 float og[8], ov[8];
; #pragma unroll
;                 for (int bj = 0; bj < 2; ++bj)
; #pragma unroll
;                     for (int n = 0; n < 2; ++n) {
;                         f32x4 pv, nv;
;                         if (m == 0) pv = (blk > 0) ? *(const LAS f32x4*)(XB + (2 * blk - 1) * 256 + bj * 128 + chl + 4 * n) : (f32x4){0.f, 0.f, 0.f, 0.f};
;                         if (m == 3) nv = (blk < 3) ? *(const LAS f32x4*)(XB + (2 * blk + 2) * 256 + bj * 128 + chl + 4 * n) : (f32x4){0.f, 0.f, 0.f, 0.f};
; #pragma unroll
;                         for (int e = 0; e < 4; ++e) {
;                             const float cur = acc[ai][bj][m][n][e];
;                             const float upB = (m == 0) ? pv[e] : dppf(0.f, acc[ai][bj][m == 0 ? 0 : m - 1][n][e], 0);
;                             const float dnB = (m == 3) ? nv[e] : dppf(0.f, acc[ai][bj][m == 3 ? 3 : m + 1][n][e], 1);
;                             const float up = dppf(upB, cur, 2), dn = dppf(dnB, cur, 3);
;                             const int k = 4 * n + e;
;                             if (bj == 0) og[k] = wg[0][k] * up + wg[1][k] * cur + wg[2][k] * dn;
;                             else         ov[k] = wv[0][k] * up + wv[1][k] * cur + wv[2][k] * dn;
;                         }
;                     }
;                 u32x4 ow;
; #pragma unroll
;                 for (int e2 = 0; e2 < 4; ++e2) ow[e2] = pk2(gelu_tanh(og[2 * e2]) * ov[2 * e2], gelu_tanh(og[2 * e2 + 1]) * ov[2 * e2 + 1]);
;                 if (trow != 0 && trow != 255) *(u32x4*)(ACTp + (size_t)(u.pm * BM + trow) * DFF + ch) = ow;
	v_mov_b32_dpp v120, v52 row_ror:1 row_mask:0xf bank_mask:0xf
	v_mov_b32_dpp v121, v53 row_ror:1 row_mask:0xf bank_mask:0xf
	v_pk_fma_f32 v[58:59], v[106:107], v[58:59], v[62:63]
	v_pk_mul_f32 v[56:57], v[60:61], v[56:57]
	v_mov_b32_dpp v52, v24 row_ror:15 row_mask:0xf bank_mask:0xf
	v_mov_b32_dpp v120, v40 row_shr:1 row_mask:0xf bank_mask:0xf
	v_mov_b32_dpp v53, v25 row_ror:15 row_mask:0xf bank_mask:0xf
	v_mov_b32_dpp v121, v41 row_shr:1 row_mask:0xf bank_mask:0xf
	v_pk_mul_f32 v[56:57], v[56:57], v[58:59]
	v_pk_mul_f32 v[58:59], v[40:41], v[96:97]
	v_mov_b32_dpp v52, v40 row_shl:1 row_mask:0xf bank_mask:0xf
	v_mov_b32_dpp v53, v41 row_shl:1 row_mask:0xf bank_mask:0xf
	v_pk_fma_f32 v[58:59], v[88:89], v[120:121], v[58:59]
	v_pk_fma_f32 v[52:53], v[92:93], v[52:53], v[58:59]
	v_mul_f32_e32 v58, 0x3d372713, v52
	v_mul_f32_e32 v58, v52, v58
	v_fma_f32 v58, v52, v58, v52
	v_mul_f32_e32 v58, 0xc0135761, v58
	v_exp_f32_e32 v60, v58
	v_mul_f32_e32 v58, 0x3d372713, v53
	v_mul_f32_e32 v58, v53, v58
	v_fma_f32 v58, v53, v58, v53
	v_mov_b32_dpp v128, v48 row_ror:1 row_mask:0xf bank_mask:0xf
	v_mov_b32_dpp v129, v49 row_ror:1 row_mask:0xf bank_mask:0xf
	v_mul_f32_e32 v58, 0xc0135761, v58
	v_mov_b32_dpp v48, v16 row_ror:15 row_mask:0xf bank_mask:0xf
	v_mov_b32_dpp v128, v32 row_shr:1 row_mask:0xf bank_mask:0xf
	v_mov_b32_dpp v49, v17 row_ror:15 row_mask:0xf bank_mask:0xf
	v_mov_b32_dpp v129, v33 row_shr:1 row_mask:0xf bank_mask:0xf
	v_exp_f32_e32 v61, v58
	v_pk_mul_f32 v[58:59], v[32:33], v[72:73]
	v_mov_b32_dpp v122, v54 row_ror:1 row_mask:0xf bank_mask:0xf
	v_mov_b32_dpp v123, v55 row_ror:1 row_mask:0xf bank_mask:0xf
	v_mov_b32_dpp v48, v32 row_shl:1 row_mask:0xf bank_mask:0xf
	v_mov_b32_dpp v49, v33 row_shl:1 row_mask:0xf bank_mask:0xf
	v_pk_fma_f32 v[58:59], v[64:65], v[128:129], v[58:59]
	v_mov_b32_dpp v54, v26 row_ror:15 row_mask:0xf bank_mask:0xf
	v_mov_b32_dpp v122, v42 row_shr:1 row_mask:0xf bank_mask:0xf
	v_mov_b32_dpp v55, v27 row_ror:15 row_mask:0xf bank_mask:0xf
	v_mov_b32_dpp v123, v43 row_shr:1 row_mask:0xf bank_mask:0xf
	v_pk_fma_f32 v[48:49], v[68:69], v[48:49], v[58:59]
	v_pk_mul_f32 v[58:59], v[42:43], v[98:99]
	v_mov_b32_dpp v54, v42 row_shl:1 row_mask:0xf bank_mask:0xf
	v_mov_b32_dpp v55, v43 row_shl:1 row_mask:0xf bank_mask:0xf
	v_pk_fma_f32 v[58:59], v[90:91], v[122:123], v[58:59]
	v_add_f32_e32 v60, 1.0, v60
	v_pk_fma_f32 v[54:55], v[94:95], v[54:55], v[58:59]
	v_add_f32_e32 v61, 1.0, v61
	v_mul_f32_e32 v58, 0x3d372713, v54
	v_mul_f32_e32 v58, v54, v58
	v_mul_f32_e32 v59, 0x3d372713, v55
	v_fma_f32 v58, v54, v58, v54
	v_mul_f32_e32 v59, v55, v59
	v_rcp_f32_e32 v60, v60
	v_rcp_f32_e32 v61, v61
	v_mul_f32_e32 v58, 0xc0135761, v58
	v_fma_f32 v59, v55, v59, v55
	v_exp_f32_e32 v58, v58
	v_mul_f32_e32 v59, 0xc0135761, v59
	v_exp_f32_e32 v59, v59
	v_pk_mul_f32 v[52:53], v[52:53], v[60:61]
	v_pk_mul_f32 v[48:49], v[52:53], v[48:49]
	v_add_f32_e32 v52, 1.0, v58
	v_rcp_f32_e32 v58, v52
	v_add_f32_e32 v52, 1.0, v59
	v_rcp_f32_e32 v59, v52
	v_mov_b32_dpp v132, v18 row_ror:15 row_mask:0xf bank_mask:0xf
	v_mov_b32_dpp v130, v34 row_shr:1 row_mask:0xf bank_mask:0xf
	v_mov_b32_dpp v133, v19 row_ror:15 row_mask:0xf bank_mask:0xf
	v_mov_b32_dpp v131, v35 row_shr:1 row_mask:0xf bank_mask:0xf
	v_cvt_pk_bf16_f32 v50, v50, v51
	v_cvt_pk_bf16_f32 v51, v56, v57
	v_pk_mul_f32 v[56:57], v[34:35], v[74:75]
	v_mov_b32_dpp v132, v34 row_shl:1 row_mask:0xf bank_mask:0xf
	v_mov_b32_dpp v133, v35 row_shl:1 row_mask:0xf bank_mask:0xf
	v_cvt_pk_bf16_f32 v52, v48, v49
	v_pk_fma_f32 v[48:49], v[66:67], v[130:131], v[56:57]
	v_pk_mul_f32 v[54:55], v[54:55], v[58:59]
	v_pk_fma_f32 v[48:49], v[70:71], v[132:133], v[48:49]
	v_pk_mul_f32 v[48:49], v[54:55], v[48:49]
	v_cvt_pk_bf16_f32 v53, v48, v49
	v_or_b32_e32 v48, 16, v253
	v_add_u32_e32 v54, s56, v48
	v_mov_b64_e32 v[48:49], s[88:89]
	v_mad_i64_i32 v[54:55], s[18:19], v54, s80, v[48:49]
	v_lshl_add_u64 v[54:55], v[54:55], 0, v[162:163]
	global_store_dwordx4 v[54:55], v[50:53], off
	v_mov_b32_dpp v62, v32 row_ror:1 row_mask:0xf bank_mask:0xf
	v_mov_b32_dpp v63, v33 row_ror:1 row_mask:0xf bank_mask:0xf
	v_pk_mul_f32 v[32:33], v[28:29], v[84:85]
	v_mov_b32_dpp v50, v44 row_ror:1 row_mask:0xf bank_mask:0xf
	v_mov_b32_dpp v51, v45 row_ror:1 row_mask:0xf bank_mask:0xf
	v_mov_b32_dpp v44, v8 row_ror:15 row_mask:0xf bank_mask:0xf
	v_mov_b32_dpp v50, v28 row_shr:1 row_mask:0xf bank_mask:0xf
	v_mov_b32_dpp v45, v9 row_ror:15 row_mask:0xf bank_mask:0xf
	v_mov_b32_dpp v51, v29 row_shr:1 row_mask:0xf bank_mask:0xf
	v_mov_b32_dpp v44, v28 row_shl:1 row_mask:0xf bank_mask:0xf
	v_mov_b32_dpp v45, v29 row_shl:1 row_mask:0xf bank_mask:0xf
	v_pk_fma_f32 v[32:33], v[76:77], v[50:51], v[32:33]
	v_pk_fma_f32 v[32:33], v[80:81], v[44:45], v[32:33]
	v_mul_f32_e32 v44, 0x3d372713, v32
	v_mul_f32_e32 v44, v32, v44
	v_fma_f32 v44, v32, v44, v32
	v_mul_f32_e32 v44, 0xc0135761, v44
	v_exp_f32_e32 v50, v44
	v_mul_f32_e32 v44, 0x3d372713, v33
	v_mul_f32_e32 v44, v33, v44
	v_fma_f32 v44, v33, v44, v33
	v_mov_b32_dpp v58, v36 row_ror:1 row_mask:0xf bank_mask:0xf
	v_mov_b32_dpp v59, v37 row_ror:1 row_mask:0xf bank_mask:0xf
	v_mul_f32_e32 v44, 0xc0135761, v44
	v_mov_b32_dpp v36, v12 row_ror:15 row_mask:0xf bank_mask:0xf
	v_mov_b32_dpp v58, v20 row_shr:1 row_mask:0xf bank_mask:0xf
	v_mov_b32_dpp v37, v13 row_ror:15 row_mask:0xf bank_mask:0xf
	v_mov_b32_dpp v59, v21 row_shr:1 row_mask:0xf bank_mask:0xf
	v_exp_f32_e32 v51, v44
	v_pk_mul_f32 v[44:45], v[20:21], v[108:109]
	v_mov_b32_dpp v52, v46 row_ror:1 row_mask:0xf bank_mask:0xf
	v_mov_b32_dpp v53, v47 row_ror:1 row_mask:0xf bank_mask:0xf
	v_mov_b32_dpp v36, v20 row_shl:1 row_mask:0xf bank_mask:0xf
; #define LAS __attribute__((address_space(3)))
; __device__ __forceinline__ unsigned pk2(float lo, float hi) { f32x2 v = {lo, hi}; bf16x2_t b = __builtin_convertvector(v, bf16x2_t); return __builtin_bit_cast(unsigned, b); }
; __device__ __forceinline__ float gelu_tanh(float x) {
;     const float t = x + 0.044715f * x * x * x;
;     const float e = __builtin_amdgcn_exp2f(-2.f * 0.7978845608028654f * LOG2E * t);
;     return x * __builtin_amdgcn_rcpf(1.f + e);
; }
;     __device__ __forceinline__ void operator()(const f32x4 (&acc)[2][2][4][2], const Unit& u, int wr, int wc, int fr, int fq, LAS unsigned char* lds) const {
;     ...
;                 const int trow = 64 * blk + 16 * m + fr;
;                 float og[8], ov[8];
; #pragma unroll
;                 for (int bj = 0; bj < 2; ++bj)
; #pragma unroll
;                     for (int n = 0; n < 2; ++n) {
;                         f32x4 pv, nv;
;                         if (m == 0) pv = (blk > 0) ? *(const LAS f32x4*)(XB + (2 * blk - 1) * 256 + bj * 128 + chl + 4 * n) : (f32x4){0.f, 0.f, 0.f, 0.f};
;                         if (m == 3) nv = (blk < 3) ? *(const LAS f32x4*)(XB + (2 * blk + 2) * 256 + bj * 128 + chl + 4 * n) : (f32x4){0.f, 0.f, 0.f, 0.f};
; #pragma unroll
;                         for (int e = 0; e < 4; ++e) {
;                             const float cur = acc[ai][bj][m][n][e];
;                             const float upB = (m == 0) ? pv[e] : dppf(0.f, acc[ai][bj][m == 0 ? 0 : m - 1][n][e], 0);
;                             const float dnB = (m == 3) ? nv[e] : dppf(0.f, acc[ai][bj][m == 3 ? 3 : m + 1][n][e], 1);
;                             const float up = dppf(upB, cur, 2), dn = dppf(dnB, cur, 3);
;                             const int k = 4 * n + e;
;                             if (bj == 0) og[k] = wg[0][k] * up + wg[1][k] * cur + wg[2][k] * dn;
;                             else         ov[k] = wv[0][k] * up + wv[1][k] * cur + wv[2][k] * dn;
;                         }
;                     }
;                 u32x4 ow;
; #pragma unroll
;                 for (int e2 = 0; e2 < 4; ++e2) ow[e2] = pk2(gelu_tanh(og[2 * e2]) * ov[2 * e2], gelu_tanh(og[2 * e2 + 1]) * ov[2 * e2 + 1]);
;                 if (trow != 0 && trow != 255) *(u32x4*)(ACTp + (size_t)(u.pm * BM + trow) * DFF + ch) = ow;
	v_mov_b32_dpp v37, v21 row_shl:1 row_mask:0xf bank_mask:0xf
	v_pk_fma_f32 v[44:45], v[100:101], v[58:59], v[44:45]
	v_mov_b32_dpp v46, v10 row_ror:15 row_mask:0xf bank_mask:0xf
	v_mov_b32_dpp v52, v30 row_shr:1 row_mask:0xf bank_mask:0xf
	v_mov_b32_dpp v47, v11 row_ror:15 row_mask:0xf bank_mask:0xf
	v_mov_b32_dpp v53, v31 row_shr:1 row_mask:0xf bank_mask:0xf
	v_pk_fma_f32 v[36:37], v[104:105], v[36:37], v[44:45]
	v_pk_mul_f32 v[44:45], v[30:31], v[86:87]
	v_mov_b32_dpp v46, v30 row_shl:1 row_mask:0xf bank_mask:0xf
	v_mov_b32_dpp v47, v31 row_shl:1 row_mask:0xf bank_mask:0xf
	v_pk_fma_f32 v[44:45], v[78:79], v[52:53], v[44:45]
	v_add_f32_e32 v50, 1.0, v50
	v_pk_fma_f32 v[44:45], v[82:83], v[46:47], v[44:45]
	v_add_f32_e32 v51, 1.0, v51
	v_mul_f32_e32 v46, 0x3d372713, v44
	v_mul_f32_e32 v47, 0x3d372713, v45
	v_mul_f32_e32 v46, v44, v46
	v_mul_f32_e32 v47, v45, v47
	v_fma_f32 v46, v44, v46, v44
	v_fma_f32 v47, v45, v47, v45
	v_rcp_f32_e32 v50, v50
	v_rcp_f32_e32 v51, v51
	v_mul_f32_e32 v46, 0xc0135761, v46
	v_mul_f32_e32 v47, 0xc0135761, v47
	v_exp_f32_e32 v46, v46
	v_exp_f32_e32 v47, v47
	v_pk_mul_f32 v[32:33], v[32:33], v[50:51]
	v_pk_mul_f32 v[32:33], v[32:33], v[36:37]
	v_add_f32_e32 v36, 1.0, v46
	v_add_f32_e32 v37, 1.0, v47
	v_rcp_f32_e32 v36, v36
	v_rcp_f32_e32 v37, v37
	v_mov_b32_dpp v60, v38 row_ror:1 row_mask:0xf bank_mask:0xf
	v_mov_b32_dpp v61, v39 row_ror:1 row_mask:0xf bank_mask:0xf
	v_mov_b32_dpp v38, v14 row_ror:15 row_mask:0xf bank_mask:0xf
	v_mov_b32_dpp v60, v22 row_shr:1 row_mask:0xf bank_mask:0xf
	v_mov_b32_dpp v39, v15 row_ror:15 row_mask:0xf bank_mask:0xf
	v_mov_b32_dpp v61, v23 row_shr:1 row_mask:0xf bank_mask:0xf
	v_mov_b32_dpp v118, v34 row_ror:1 row_mask:0xf bank_mask:0xf
	v_mov_b32_dpp v119, v35 row_ror:1 row_mask:0xf bank_mask:0xf
	v_pk_mul_f32 v[34:35], v[22:23], v[110:111]
	v_mov_b32_dpp v38, v22 row_shl:1 row_mask:0xf bank_mask:0xf
	v_mov_b32_dpp v39, v23 row_shl:1 row_mask:0xf bank_mask:0xf
	v_pk_fma_f32 v[34:35], v[102:103], v[60:61], v[34:35]
	v_pk_fma_f32 v[34:35], v[106:107], v[38:39], v[34:35]
	v_pk_mul_f32 v[36:37], v[44:45], v[36:37]
	v_mov_b32_dpp v54, v40 row_ror:1 row_mask:0xf bank_mask:0xf
	v_mov_b32_dpp v55, v41 row_ror:1 row_mask:0xf bank_mask:0xf
	v_pk_mul_f32 v[34:35], v[36:37], v[34:35]
	v_mov_b32_dpp v40, v4 row_ror:15 row_mask:0xf bank_mask:0xf
	v_mov_b32_dpp v54, v24 row_shr:1 row_mask:0xf bank_mask:0xf
	v_mov_b32_dpp v41, v5 row_ror:15 row_mask:0xf bank_mask:0xf
	v_mov_b32_dpp v55, v25 row_shr:1 row_mask:0xf bank_mask:0xf
	v_cvt_pk_bf16_f32 v32, v32, v33
	v_cvt_pk_bf16_f32 v33, v34, v35
	v_pk_mul_f32 v[34:35], v[24:25], v[96:97]
	v_mov_b32_dpp v40, v24 row_shl:1 row_mask:0xf bank_mask:0xf
	v_mov_b32_dpp v41, v25 row_shl:1 row_mask:0xf bank_mask:0xf
	v_pk_fma_f32 v[34:35], v[88:89], v[54:55], v[34:35]
	v_pk_fma_f32 v[34:35], v[92:93], v[40:41], v[34:35]
	v_mul_f32_e32 v38, 0x3d372713, v34
	v_mul_f32_e32 v38, v34, v38
	v_fma_f32 v38, v34, v38, v34
	v_mul_f32_e32 v38, 0xc0135761, v38
	v_exp_f32_e32 v40, v38
	v_mul_f32_e32 v38, 0x3d372713, v35
	v_mul_f32_e32 v38, v35, v38
	v_fma_f32 v38, v35, v38, v35
	v_mul_f32_e32 v38, 0xc0135761, v38
	v_exp_f32_e32 v41, v38
	v_add_f32_e32 v40, 1.0, v40
	v_rcp_f32_e32 v40, v40
	v_mov_b32_dpp v56, v42 row_ror:1 row_mask:0xf bank_mask:0xf
	v_add_f32_e32 v41, 1.0, v41
	v_rcp_f32_e32 v41, v41
	v_mov_b32_dpp v57, v43 row_ror:1 row_mask:0xf bank_mask:0xf
	v_mov_b32_dpp v42, v6 row_ror:15 row_mask:0xf bank_mask:0xf
	v_mov_b32_dpp v56, v26 row_shr:1 row_mask:0xf bank_mask:0xf
	v_mov_b32_dpp v43, v7 row_ror:15 row_mask:0xf bank_mask:0xf
	v_mov_b32_dpp v57, v27 row_shr:1 row_mask:0xf bank_mask:0xf
	v_pk_mul_f32 v[44:45], v[26:27], v[98:99]
	v_mov_b32_dpp v42, v26 row_shl:1 row_mask:0xf bank_mask:0xf
	v_mov_b32_dpp v43, v27 row_shl:1 row_mask:0xf bank_mask:0xf
	v_pk_mul_f32 v[34:35], v[34:35], v[40:41]
	v_pk_fma_f32 v[40:41], v[90:91], v[56:57], v[44:45]
	v_pk_fma_f32 v[40:41], v[94:95], v[42:43], v[40:41]
	v_mul_f32_e32 v42, 0x3d372713, v40
	v_mul_f32_e32 v43, 0x3d372713, v41
	v_mul_f32_e32 v42, v40, v42
	v_mul_f32_e32 v43, v41, v43
	v_fma_f32 v42, v40, v42, v40
	v_fma_f32 v43, v41, v43, v41
	v_mul_f32_e32 v42, 0xc0135761, v42
	v_mul_f32_e32 v43, 0xc0135761, v43
	v_exp_f32_e32 v42, v42
	v_exp_f32_e32 v43, v43
	v_mov_b32_dpp v116, v0 row_ror:15 row_mask:0xf bank_mask:0xf
	v_mov_b32_dpp v62, v16 row_shr:1 row_mask:0xf bank_mask:0xf
	v_mov_b32_dpp v117, v1 row_ror:15 row_mask:0xf bank_mask:0xf
	v_mov_b32_dpp v63, v17 row_shr:1 row_mask:0xf bank_mask:0xf
	v_pk_mul_f32 v[38:39], v[16:17], v[72:73]
	v_mov_b32_dpp v116, v16 row_shl:1 row_mask:0xf bank_mask:0xf
	v_mov_b32_dpp v117, v17 row_shl:1 row_mask:0xf bank_mask:0xf
	v_pk_fma_f32 v[38:39], v[64:65], v[62:63], v[38:39]
	v_pk_fma_f32 v[38:39], v[68:69], v[116:117], v[38:39]
	v_pk_mul_f32 v[34:35], v[34:35], v[38:39]
	v_add_f32_e32 v38, 1.0, v42
	v_add_f32_e32 v39, 1.0, v43
	v_rcp_f32_e32 v38, v38
	v_rcp_f32_e32 v39, v39
	v_mov_b32_dpp v120, v2 row_ror:15 row_mask:0xf bank_mask:0xf
	v_mov_b32_dpp v118, v18 row_shr:1 row_mask:0xf bank_mask:0xf
	v_mov_b32_dpp v121, v3 row_ror:15 row_mask:0xf bank_mask:0xf
	v_mov_b32_dpp v119, v19 row_shr:1 row_mask:0xf bank_mask:0xf
	v_pk_mul_f32 v[36:37], v[18:19], v[74:75]
	v_mov_b32_dpp v120, v18 row_shl:1 row_mask:0xf bank_mask:0xf
	v_mov_b32_dpp v121, v19 row_shl:1 row_mask:0xf bank_mask:0xf
	v_pk_fma_f32 v[36:37], v[66:67], v[118:119], v[36:37]
	v_pk_mul_f32 v[38:39], v[40:41], v[38:39]
	v_pk_fma_f32 v[36:37], v[70:71], v[120:121], v[36:37]
	v_cvt_pk_bf16_f32 v34, v34, v35
	v_pk_mul_f32 v[36:37], v[38:39], v[36:37]
	v_mov_b32_e32 v114, 0
	v_cvt_pk_bf16_f32 v35, v36, v37
	v_or_b32_e32 v36, 32, v253
	v_add_u32_e32 v36, s56, v36
	v_mad_i64_i32 v[36:37], s[18:19], v36, s80, v[48:49]
	v_lshl_add_u64 v[36:37], v[36:37], 0, v[162:163]
	global_store_dwordx4 v[36:37], v[32:35], off
	s_andn2_b64 vcc, exec, s[44:45]
	s_nop 0
	v_cndmask_b32_e64 v32, 0, 1, s[44:45]
	v_cmp_ne_u32_e64 s[18:19], 1, v32
	v_mov_b32_e32 v32, 0
	v_mov_b32_e32 v33, 0
	v_mov_b32_e32 v34, 0
	v_mov_b32_e32 v35, 0
	s_cbranch_vccnz .LBB0_1198
	ds_read_b128 v[32:35], v249 offset:2048
; #define LAS __attribute__((address_space(3)))
; __device__ __forceinline__ unsigned pk2(float lo, float hi) { f32x2 v = {lo, hi}; bf16x2_t b = __builtin_convertvector(v, bf16x2_t); return __builtin_bit_cast(unsigned, b); }
;     __device__ __forceinline__ void operator()(const f32x4 (&acc)[2][2][4][2], const Unit& u, int wr, int wc, int fr, int fq, LAS unsigned char* lds) const {
;     ...
;                 const int trow = 64 * blk + 16 * m + fr;
;                 float og[8], ov[8];
; #pragma unroll
;                 for (int bj = 0; bj < 2; ++bj)
; #pragma unroll
;                     for (int n = 0; n < 2; ++n) {
;                         f32x4 pv, nv;
;                         if (m == 0) pv = (blk > 0) ? *(const LAS f32x4*)(XB + (2 * blk - 1) * 256 + bj * 128 + chl + 4 * n) : (f32x4){0.f, 0.f, 0.f, 0.f};
;                         if (m == 3) nv = (blk < 3) ? *(const LAS f32x4*)(XB + (2 * blk + 2) * 256 + bj * 128 + chl + 4 * n) : (f32x4){0.f, 0.f, 0.f, 0.f};
; #pragma unroll
;                         for (int e = 0; e < 4; ++e) {
;                             const float cur = acc[ai][bj][m][n][e];
;                             const float upB = (m == 0) ? pv[e] : dppf(0.f, acc[ai][bj][m == 0 ? 0 : m - 1][n][e], 0);
;                             const float dnB = (m == 3) ? nv[e] : dppf(0.f, acc[ai][bj][m == 3 ? 3 : m + 1][n][e], 1);
;                             const float up = dppf(upB, cur, 2), dn = dppf(dnB, cur, 3);
;                             const int k = 4 * n + e;
;                             if (bj == 0) og[k] = wg[0][k] * up + wg[1][k] * cur + wg[2][k] * dn;
;                             else         ov[k] = wv[0][k] * up + wv[1][k] * cur + wv[2][k] * dn;
;                         }
;                     }
;                 u32x4 ow;
; #pragma unroll
;                 for (int e2 = 0; e2 < 4; ++e2) ow[e2] = pk2(gelu_tanh(og[2 * e2]) * ov[2 * e2], gelu_tanh(og[2 * e2 + 1]) * ov[2 * e2 + 1]);
;                 if (trow != 0 && trow != 255) *(u32x4*)(ACTp + (size_t)(u.pm * BM + trow) * DFF + ch) = ow;
.LBB0_1198:
	v_mov_b32_dpp v36, v28 row_ror:1 row_mask:0xf bank_mask:0xf
	v_mov_b32_dpp v37, v29 row_ror:1 row_mask:0xf bank_mask:0xf
	v_mov_b32_dpp v38, v30 row_ror:1 row_mask:0xf bank_mask:0xf
	v_mov_b32_dpp v39, v31 row_ror:1 row_mask:0xf bank_mask:0xf
	v_mov_b32_dpp v36, v8 row_shr:1 row_mask:0xf bank_mask:0xf
	s_waitcnt lgkmcnt(0)
	v_mov_b32_dpp v32, v8 row_shl:1 row_mask:0xf bank_mask:0xf
	v_mov_b32_dpp v37, v9 row_shr:1 row_mask:0xf bank_mask:0xf
	v_mov_b32_dpp v33, v9 row_shl:1 row_mask:0xf bank_mask:0xf
	v_mov_b32_dpp v38, v10 row_shr:1 row_mask:0xf bank_mask:0xf
	v_mov_b32_dpp v34, v10 row_shl:1 row_mask:0xf bank_mask:0xf
	v_mov_b32_dpp v39, v11 row_shr:1 row_mask:0xf bank_mask:0xf
	v_mov_b32_dpp v35, v11 row_shl:1 row_mask:0xf bank_mask:0xf
	s_and_b64 vcc, exec, s[18:19]
	v_mov_b32_e32 v115, 0
	v_mov_b32_e32 v116, 0
	v_mov_b32_e32 v117, 0
	s_cbranch_vccnz .LBB0_1200
	ds_read_b128 v[114:117], v249 offset:2064
.LBB0_1200:
	v_mov_b32_dpp v40, v24 row_ror:1 row_mask:0xf bank_mask:0xf
	v_mov_b32_dpp v41, v25 row_ror:1 row_mask:0xf bank_mask:0xf
	v_mov_b32_dpp v42, v26 row_ror:1 row_mask:0xf bank_mask:0xf
	v_mov_b32_dpp v43, v27 row_ror:1 row_mask:0xf bank_mask:0xf
	v_mov_b32_e32 v28, 0
	v_mov_b32_dpp v40, v4 row_shr:1 row_mask:0xf bank_mask:0xf
	s_waitcnt lgkmcnt(0)
	v_mov_b32_dpp v114, v4 row_shl:1 row_mask:0xf bank_mask:0xf
	v_mov_b32_dpp v41, v5 row_shr:1 row_mask:0xf bank_mask:0xf
	v_mov_b32_dpp v115, v5 row_shl:1 row_mask:0xf bank_mask:0xf
	v_mov_b32_dpp v42, v6 row_shr:1 row_mask:0xf bank_mask:0xf
	v_mov_b32_dpp v116, v6 row_shl:1 row_mask:0xf bank_mask:0xf
	v_mov_b32_dpp v43, v7 row_shr:1 row_mask:0xf bank_mask:0xf
	v_mov_b32_dpp v117, v7 row_shl:1 row_mask:0xf bank_mask:0xf
	s_and_b64 vcc, exec, s[18:19]
	v_mov_b32_e32 v24, 0
	v_mov_b32_e32 v25, 0
	v_mov_b32_e32 v26, 0
	v_mov_b32_e32 v27, 0
	s_cbranch_vccnz .LBB0_1202
	ds_read_b128 v[24:27], v249 offset:2560
.LBB0_1202:
	v_mov_b32_dpp v44, v20 row_ror:1 row_mask:0xf bank_mask:0xf
	v_mov_b32_dpp v45, v21 row_ror:1 row_mask:0xf bank_mask:0xf
	v_mov_b32_dpp v46, v22 row_ror:1 row_mask:0xf bank_mask:0xf
	v_mov_b32_dpp v47, v23 row_ror:1 row_mask:0xf bank_mask:0xf
	v_mov_b32_dpp v44, v12 row_shr:1 row_mask:0xf bank_mask:0xf
	s_waitcnt lgkmcnt(0)
	v_mov_b32_dpp v24, v12 row_shl:1 row_mask:0xf bank_mask:0xf
	v_mov_b32_dpp v45, v13 row_shr:1 row_mask:0xf bank_mask:0xf
	v_mov_b32_dpp v25, v13 row_shl:1 row_mask:0xf bank_mask:0xf
	v_mov_b32_dpp v46, v14 row_shr:1 row_mask:0xf bank_mask:0xf
	v_mov_b32_dpp v26, v14 row_shl:1 row_mask:0xf bank_mask:0xf
	v_mov_b32_dpp v47, v15 row_shr:1 row_mask:0xf bank_mask:0xf
	v_mov_b32_dpp v27, v15 row_shl:1 row_mask:0xf bank_mask:0xf
	s_and_b64 vcc, exec, s[18:19]
	v_mov_b32_e32 v29, 0
	v_mov_b32_e32 v30, 0
	v_mov_b32_e32 v31, 0
	s_cbranch_vccnz .LBB0_1204
	ds_read_b128 v[28:31], v249 offset:2576
; #define LAS __attribute__((address_space(3)))
; __device__ __forceinline__ unsigned pk2(float lo, float hi) { f32x2 v = {lo, hi}; bf16x2_t b = __builtin_convertvector(v, bf16x2_t); return __builtin_bit_cast(unsigned, b); }
; __device__ __forceinline__ float gelu_tanh(float x) {
;     const float t = x + 0.044715f * x * x * x;
;     const float e = __builtin_amdgcn_exp2f(-2.f * 0.7978845608028654f * LOG2E * t);
;     return x * __builtin_amdgcn_rcpf(1.f + e);
; }
;     __device__ __forceinline__ void operator()(const f32x4 (&acc)[2][2][4][2], const Unit& u, int wr, int wc, int fr, int fq, LAS unsigned char* lds) const {
;     ...
;                 const int trow = 64 * blk + 16 * m + fr;
;                 float og[8], ov[8];
; #pragma unroll
;                 for (int bj = 0; bj < 2; ++bj)
; #pragma unroll
;                     for (int n = 0; n < 2; ++n) {
;                         f32x4 pv, nv;
;                         if (m == 0) pv = (blk > 0) ? *(const LAS f32x4*)(XB + (2 * blk - 1) * 256 + bj * 128 + chl + 4 * n) : (f32x4){0.f, 0.f, 0.f, 0.f};
;                         if (m == 3) nv = (blk < 3) ? *(const LAS f32x4*)(XB + (2 * blk + 2) * 256 + bj * 128 + chl + 4 * n) : (f32x4){0.f, 0.f, 0.f, 0.f};
; #pragma unroll
;                         for (int e = 0; e < 4; ++e) {
;                             const float cur = acc[ai][bj][m][n][e];
;                             const float upB = (m == 0) ? pv[e] : dppf(0.f, acc[ai][bj][m == 0 ? 0 : m - 1][n][e], 0);
;                             const float dnB = (m == 3) ? nv[e] : dppf(0.f, acc[ai][bj][m == 3 ? 3 : m + 1][n][e], 1);
;                             const float up = dppf(upB, cur, 2), dn = dppf(dnB, cur, 3);
;                             const int k = 4 * n + e;
;                             if (bj == 0) og[k] = wg[0][k] * up + wg[1][k] * cur + wg[2][k] * dn;
;                             else         ov[k] = wv[0][k] * up + wv[1][k] * cur + wv[2][k] * dn;
;                         }
;                     }
;                 u32x4 ow;
; #pragma unroll
;                 for (int e2 = 0; e2 < 4; ++e2) ow[e2] = pk2(gelu_tanh(og[2 * e2]) * ov[2 * e2], gelu_tanh(og[2 * e2 + 1]) * ov[2 * e2 + 1]);
;                 if (trow != 0 && trow != 255) *(u32x4*)(ACTp + (size_t)(u.pm * BM + trow) * DFF + ch) = ow;
.LBB0_1204:
	s_waitcnt lgkmcnt(0)
	v_mov_b32_dpp v28, v0 row_shl:1 row_mask:0xf bank_mask:0xf
	v_mov_b32_dpp v20, v16 row_ror:1 row_mask:0xf bank_mask:0xf
	v_mov_b32_dpp v21, v17 row_ror:1 row_mask:0xf bank_mask:0xf
	v_mov_b32_dpp v20, v0 row_shr:1 row_mask:0xf bank_mask:0xf
	v_mov_b32_dpp v16, v18 row_ror:1 row_mask:0xf bank_mask:0xf
	v_mov_b32_dpp v17, v19 row_ror:1 row_mask:0xf bank_mask:0xf
	v_mov_b32_dpp v21, v1 row_shr:1 row_mask:0xf bank_mask:0xf
	v_mov_b32_dpp v29, v1 row_shl:1 row_mask:0xf bank_mask:0xf
	v_mov_b32_dpp v16, v2 row_shr:1 row_mask:0xf bank_mask:0xf
	v_mov_b32_dpp v30, v2 row_shl:1 row_mask:0xf bank_mask:0xf
	v_mov_b32_dpp v17, v3 row_shr:1 row_mask:0xf bank_mask:0xf
	v_mov_b32_dpp v31, v3 row_shl:1 row_mask:0xf bank_mask:0xf
	s_and_saveexec_b64 s[18:19], s[14:15]
	s_cbranch_execz .LBB0_1206
	v_pk_mul_f32 v[8:9], v[8:9], v[84:85]
	v_pk_mul_f32 v[18:19], v[2:3], v[74:75]
	v_pk_fma_f32 v[8:9], v[76:77], v[36:37], v[8:9]
	v_pk_mul_f32 v[10:11], v[10:11], v[86:87]
	v_pk_fma_f32 v[8:9], v[80:81], v[32:33], v[8:9]
	v_pk_fma_f32 v[10:11], v[78:79], v[38:39], v[10:11]
	v_mul_f32_e32 v2, 0x3d372713, v8
	v_mul_f32_e32 v2, v8, v2
	v_fma_f32 v2, v8, v2, v8
	v_mul_f32_e32 v2, 0xc0135761, v2
	v_exp_f32_e32 v22, v2
	v_mul_f32_e32 v2, 0x3d372713, v9
	v_mul_f32_e32 v2, v9, v2
	v_fma_f32 v2, v9, v2, v9
	v_mul_f32_e32 v2, 0xc0135761, v2
	v_exp_f32_e32 v23, v2
	v_pk_fma_f32 v[10:11], v[82:83], v[34:35], v[10:11]
	v_pk_mul_f32 v[2:3], v[0:1], v[72:73]
	v_add_f32_e32 v0, 1.0, v22
	v_add_f32_e32 v1, 1.0, v23
	v_mul_f32_e32 v22, 0x3d372713, v10
	v_mul_f32_e32 v23, 0x3d372713, v11
	v_mul_f32_e32 v22, v10, v22
	v_mul_f32_e32 v23, v11, v23
	v_fma_f32 v22, v10, v22, v10
	v_fma_f32 v23, v11, v23, v11
	v_mul_f32_e32 v22, 0xc0135761, v22
	v_mul_f32_e32 v23, 0xc0135761, v23
	v_exp_f32_e32 v22, v22
	v_exp_f32_e32 v23, v23
	v_rcp_f32_e32 v0, v0
	v_rcp_f32_e32 v1, v1
	v_pk_mul_f32 v[12:13], v[12:13], v[108:109]
	v_add_f32_e32 v22, 1.0, v22
	v_add_f32_e32 v23, 1.0, v23
	v_pk_fma_f32 v[12:13], v[100:101], v[44:45], v[12:13]
	v_pk_mul_f32 v[4:5], v[4:5], v[96:97]
	v_rcp_f32_e32 v22, v22
	v_rcp_f32_e32 v23, v23
	v_pk_fma_f32 v[12:13], v[104:105], v[24:25], v[12:13]
	v_pk_fma_f32 v[4:5], v[88:89], v[40:41], v[4:5]
	v_pk_mul_f32 v[0:1], v[8:9], v[0:1]
	v_pk_fma_f32 v[4:5], v[92:93], v[114:115], v[4:5]
	v_pk_mul_f32 v[0:1], v[0:1], v[12:13]
	v_pk_mul_f32 v[8:9], v[10:11], v[22:23]
	v_cvt_pk_bf16_f32 v0, v0, v1
	v_mul_f32_e32 v1, 0x3d372713, v4
	v_mul_f32_e32 v1, v4, v1
	v_mul_f32_e32 v10, 0x3d372713, v5
	v_fma_f32 v1, v4, v1, v4
	v_mul_f32_e32 v10, v5, v10
	v_mul_f32_e32 v1, 0xc0135761, v1
	v_fma_f32 v10, v5, v10, v5
	v_exp_f32_e32 v1, v1
	v_mul_f32_e32 v10, 0xc0135761, v10
	v_exp_f32_e32 v11, v10
	v_pk_mul_f32 v[14:15], v[14:15], v[110:111]
	v_pk_mul_f32 v[6:7], v[6:7], v[98:99]
	v_pk_fma_f32 v[14:15], v[102:103], v[46:47], v[14:15]
	v_pk_fma_f32 v[6:7], v[90:91], v[42:43], v[6:7]
	v_pk_fma_f32 v[14:15], v[106:107], v[26:27], v[14:15]
	v_add_f32_e32 v1, 1.0, v1
	v_pk_fma_f32 v[6:7], v[94:95], v[116:117], v[6:7]
	v_pk_mul_f32 v[8:9], v[8:9], v[14:15]
	v_rcp_f32_e32 v10, v1
	v_add_f32_e32 v1, 1.0, v11
	v_rcp_f32_e32 v11, v1
	v_cvt_pk_bf16_f32 v1, v8, v9
	v_mul_f32_e32 v8, 0x3d372713, v6
	v_mul_f32_e32 v9, 0x3d372713, v7
	v_mul_f32_e32 v8, v6, v8
	v_mul_f32_e32 v9, v7, v9
	v_fma_f32 v8, v6, v8, v6
	v_fma_f32 v9, v7, v9, v7
	v_mul_f32_e32 v8, 0xc0135761, v8
	v_mul_f32_e32 v9, 0xc0135761, v9
	v_exp_f32_e32 v8, v8
	v_exp_f32_e32 v9, v9
	v_pk_fma_f32 v[2:3], v[64:65], v[20:21], v[2:3]
	v_pk_mul_f32 v[4:5], v[4:5], v[10:11]
	v_pk_fma_f32 v[2:3], v[68:69], v[28:29], v[2:3]
	s_nop 0
	v_pk_mul_f32 v[2:3], v[4:5], v[2:3]
	v_add_f32_e32 v4, 1.0, v8
	v_add_f32_e32 v5, 1.0, v9
	v_rcp_f32_e32 v4, v4
	v_rcp_f32_e32 v5, v5
	v_pk_fma_f32 v[8:9], v[66:67], v[16:17], v[18:19]
	v_cvt_pk_bf16_f32 v2, v2, v3
	v_pk_fma_f32 v[8:9], v[70:71], v[30:31], v[8:9]
	v_pk_mul_f32 v[4:5], v[6:7], v[4:5]
	s_nop 0
	v_pk_mul_f32 v[4:5], v[4:5], v[8:9]
	s_nop 0
	v_cvt_pk_bf16_f32 v3, v4, v5
	v_or_b32_e32 v4, 48, v253
	v_add_u32_e32 v6, s56, v4
	v_mov_b64_e32 v[4:5], s[88:89]
	v_mad_i64_i32 v[4:5], s[54:55], v6, s80, v[4:5]
	v_lshl_add_u64 v[4:5], v[216:217], 1, v[4:5]
	global_store_dwordx4 v[4:5], v[0:3], off
